# prologue de-serialisation in phase 0: first x batch requested before the narrow-weight set-up; no store drain at entry
# baseline (speedup 1.0000x reference)
.LBB0_123:
	s_waitcnt lgkmcnt(0)
	s_barrier
	v_lshrrev_b32_e32 v196, 6, v198
	v_and_b32_e32 v197, 63, v198
	v_mbcnt_lo_u32_b32 v194, -1, 0
	v_lshlrev_b32_e32 v166, 4, v197
	v_lshlrev_b32_e32 v164, 3, v197
	v_writelane_b32 v236, s92, 38
	v_writelane_b32 v236, s93, 39
	v_writelane_b32 v236, s96, 40
	v_readlane_b32 s4, v236, 3
	v_readlane_b32 s5, v236, 4
	v_readlane_b32 s8, v236, 5
	v_readlane_b32 s9, v236, 6
	v_readlane_b32 s10, v236, 7
	v_readlane_b32 s11, v236, 8
	v_readlane_b32 s36, v236, 11
	v_readlane_b32 s37, v236, 12
	v_readlane_b32 s38, v236, 13
	v_readlane_b32 s39, v236, 14
	v_readlane_b32 s12, v236, 22
	v_readlane_b32 s13, v236, 23
	v_readlane_b32 s14, v236, 24
	v_readlane_b32 s15, v236, 25
	v_readlane_b32 s18, v236, 26
	v_readlane_b32 s19, v236, 27
	s_mov_b32 s6, s64
	s_mov_b32 s7, s65
	s_nop 3
	s_cmp_lt_u32 s96, 128
	s_cbranch_scc0 .Lp0_nokm
	s_lshl_b32 s20, s96, 11
	s_add_u32 s18, s18, s20
	s_addc_u32 s19, s19, 0
	v_lshlrev_b32_e32 v0, 2, v198
	v_mov_b32_e32 v1, 0
	global_store_dword v0, v1, s[18:19]
.Lp0_nokm:
	v_readfirstlane_b32 s18, v196
	s_lshl_b32 s16, s96, 6
	s_lshl_b32 s18, s18, 3
	s_add_u32 s16, s16, s18
	s_lshl_b32 s18, s16, 13
	s_add_u32 s22, s4, s18
	s_addc_u32 s23, s5, 0
	s_add_u32 s32, s22, 0x1000
	s_addc_u32 s33, s23, 0
	global_load_dwordx4 v[64:67], v166, s[22:23] offset:0
	global_load_dwordx4 v[68:71], v166, s[22:23] offset:1024
	global_load_dwordx4 v[72:75], v166, s[22:23] offset:2048
	global_load_dwordx4 v[76:79], v166, s[22:23] offset:3072
	global_load_dwordx4 v[80:83], v166, s[32:33] offset:0
	global_load_dwordx4 v[84:87], v166, s[32:33] offset:1024
	global_load_dwordx4 v[88:91], v166, s[32:33] offset:2048
	global_load_dwordx4 v[92:95], v166, s[32:33] offset:3072
	s_add_u32 s22, s22, 0x2000
	s_addc_u32 s23, s23, 0
	s_add_u32 s32, s22, 0x1000
	s_addc_u32 s33, s23, 0
	global_load_dwordx4 v[96:99], v166, s[22:23] offset:0
	global_load_dwordx4 v[100:103], v166, s[22:23] offset:1024
	global_load_dwordx4 v[104:107], v166, s[22:23] offset:2048
	global_load_dwordx4 v[108:111], v166, s[22:23] offset:3072
	global_load_dwordx4 v[112:115], v166, s[32:33] offset:0
	global_load_dwordx4 v[116:119], v166, s[32:33] offset:1024
	global_load_dwordx4 v[120:123], v166, s[32:33] offset:2048
	global_load_dwordx4 v[124:127], v166, s[32:33] offset:3072
	v_lshrrev_b32_e32 v0, 2, v198
	s_mov_b32 s20, 0xc040
	v_mul_lo_u32 v0, v0, s20
	v_and_b32_e32 v1, 3, v198
	v_lshl_add_u32 v0, v1, 4, v0
	s_add_u32 s18, s10, 0x4000
	s_addc_u32 s19, s11, 0
	global_load_dwordx4 v[4:7], v0, s[18:19]
	s_add_u32 s18, s18, 0x602000
	s_addc_u32 s19, s19, 0
	global_load_dwordx4 v[8:11], v0, s[18:19]
	s_add_u32 s18, s18, 0x602000
	s_addc_u32 s19, s19, 0
	global_load_dwordx4 v[12:15], v0, s[18:19]
	s_add_u32 s18, s18, 0x602000
	s_addc_u32 s19, s19, 0
	global_load_dwordx4 v[16:19], v0, s[18:19]
	s_add_u32 s18, s18, 0x602000
	s_addc_u32 s19, s19, 0
	global_load_dwordx4 v[20:23], v0, s[18:19]
	s_add_u32 s18, s18, 0x602000
	s_addc_u32 s19, s19, 0
	global_load_dwordx4 v[24:27], v0, s[18:19]
	s_add_u32 s18, s18, 0x602000
	s_addc_u32 s19, s19, 0
	global_load_dwordx4 v[28:31], v0, s[18:19]
	s_add_u32 s18, s18, 0x602000
	s_addc_u32 s19, s19, 0
	global_load_dwordx4 v[32:35], v0, s[18:19]
	s_add_u32 s18, s18, 0x602000
	s_addc_u32 s19, s19, 0
	global_load_dwordx4 v[36:39], v0, s[18:19]
	s_add_u32 s18, s18, 0x602000
	s_addc_u32 s19, s19, 0
	global_load_dwordx4 v[40:43], v0, s[18:19]
	s_add_u32 s18, s18, 0x602000
	s_addc_u32 s19, s19, 0
	global_load_dwordx4 v[44:47], v0, s[18:19]
	s_add_u32 s18, s18, 0x602000
	s_addc_u32 s19, s19, 0
	global_load_dwordx4 v[48:51], v0, s[18:19]
	s_add_u32 s18, s18, 0x602000
	s_addc_u32 s19, s19, 0
	global_load_dwordx4 v[52:55], v0, s[18:19]
	s_add_u32 s18, s18, 0x602000
	s_addc_u32 s19, s19, 0
	global_load_dwordx4 v[56:59], v0, s[18:19]
	s_add_u32 s18, s18, 0x602000
	s_addc_u32 s19, s19, 0
	global_load_dwordx4 v[60:63], v0, s[18:19]
	s_add_u32 s18, s18, 0x602000
	s_addc_u32 s19, s19, 0
	global_load_dwordx4 v[128:131], v0, s[18:19]
	s_add_u32 s32, s8, 0x1000
	s_addc_u32 s33, s9, 0
	global_load_dwordx4 v[200:203], v166, s[8:9] offset:0
	global_load_dwordx4 v[204:207], v166, s[8:9] offset:1024
	global_load_dwordx4 v[208:211], v166, s[8:9] offset:2048
	global_load_dwordx4 v[212:215], v166, s[8:9] offset:3072
	global_load_dwordx4 v[216:219], v166, s[32:33] offset:0
	global_load_dwordx4 v[220:223], v166, s[32:33] offset:1024
	global_load_dwordx4 v[224:227], v166, s[32:33] offset:2048
	global_load_dwordx4 v[228:231], v166, s[32:33] offset:3072
	v_bfe_u32 v2, v198, 2, 2
	v_lshrrev_b32_e32 v3, 4, v198
	v_lshl_add_u32 v2, v2, 6, v3
	v_lshlrev_b32_e32 v2, 6, v2
	v_add_u32_e32 v3, v1, v196
	v_and_b32_e32 v3, 3, v3
	v_lshl_add_u32 v2, v3, 4, v2
	s_waitcnt vmcnt(23)
	ds_write_b128 v2, v[4:7] offset:0
	s_waitcnt vmcnt(22)
	ds_write_b128 v2, v[8:11] offset:2048
	s_waitcnt vmcnt(21)
	ds_write_b128 v2, v[12:15] offset:16384
	s_waitcnt vmcnt(20)
	ds_write_b128 v2, v[16:19] offset:18432
	s_waitcnt vmcnt(19)
	ds_write_b128 v2, v[20:23] offset:32768
	s_waitcnt vmcnt(18)
	ds_write_b128 v2, v[24:27] offset:34816
	s_waitcnt vmcnt(17)
	ds_write_b128 v2, v[28:31] offset:49152
	s_waitcnt vmcnt(16)
	ds_write_b128 v2, v[32:35] offset:51200
	s_waitcnt vmcnt(15)
	v_add_u32_e32 v3, 0x10000, v2
	ds_write_b128 v3, v[36:39] offset:0
	s_waitcnt vmcnt(14)
	ds_write_b128 v3, v[40:43] offset:2048
	s_waitcnt vmcnt(13)
	ds_write_b128 v3, v[44:47] offset:16384
	s_waitcnt vmcnt(12)
	ds_write_b128 v3, v[48:51] offset:18432
	s_waitcnt vmcnt(11)
	ds_write_b128 v3, v[52:55] offset:32768
	s_waitcnt vmcnt(10)
	ds_write_b128 v3, v[56:59] offset:34816
	s_waitcnt vmcnt(9)
	ds_write_b128 v3, v[60:63] offset:49152
	s_waitcnt vmcnt(8)
	ds_write_b128 v3, v[128:131] offset:51200
	v_lshrrev_b32_e32 v0, 2, v197
	v_add_u32_e32 v1, 0, v0
	v_and_b32_e32 v1, 3, v1
	v_lshlrev_b32_e32 v1, 4, v1
	v_lshl_add_u32 v244, v197, 6, v1
	v_add_u32_e32 v248, 0x10000, v244
	v_add_u32_e32 v1, 1, v0
	v_and_b32_e32 v1, 3, v1
	v_lshlrev_b32_e32 v1, 4, v1
	v_lshl_add_u32 v245, v197, 6, v1
	v_add_u32_e32 v249, 0x10000, v245
	v_add_u32_e32 v1, 2, v0
	v_and_b32_e32 v1, 3, v1
	v_lshlrev_b32_e32 v1, 4, v1
	v_lshl_add_u32 v246, v197, 6, v1
	v_add_u32_e32 v250, 0x10000, v246
	v_add_u32_e32 v1, 3, v0
	v_and_b32_e32 v1, 3, v1
	v_lshlrev_b32_e32 v1, 4, v1
	v_lshl_add_u32 v247, v197, 6, v1
	v_add_u32_e32 v251, 0x10000, v247
	v_and_b32_e32 v0, 32, v197
	v_cmp_ne_u32_e64 s[24:25], 0, v0
	v_and_b32_e32 v0, 16, v197
	v_cmp_ne_u32_e64 s[26:27], 0, v0
	v_and_b32_e32 v0, 8, v197
	v_cmp_ne_u32_e64 s[28:29], 0, v0
	v_and_b32_e32 v0, 4, v197
	v_cmp_ne_u32_e64 s[30:31], 0, v0
	v_and_b32_e32 v0, 2, v197
	v_cmp_ne_u32_e64 s[34:35], 0, v0
	v_bfe_u32 v0, v197, 1, 3
	v_lshlrev_b32_e32 v0, 2, v0
	global_load_dword v237, v0, s[36:37]
	global_load_dword v195, v0, s[38:39]
	s_waitcnt vmcnt(0) lgkmcnt(0)
	v_mul_f32_e32 v237, 0x3fb8aa3b, v237
	v_exp_f32_e32 v237, v237
	s_mov_b32 s20, 0x3a000000
	s_barrier
	s_mov_b32 s17, 0

.Lp0_nopf:
	v_mov_b32_e32 v128, 0
	v_mov_b32_e32 v129, 0
	v_mov_b32_e32 v130, 0
	v_mov_b32_e32 v131, 0
	v_mov_b32_e32 v132, 0
	v_mov_b32_e32 v133, 0
	v_mov_b32_e32 v134, 0
	v_mov_b32_e32 v135, 0
	v_mov_b32_e32 v136, 0
	v_mov_b32_e32 v137, 0
	v_mov_b32_e32 v138, 0
	v_mov_b32_e32 v139, 0
	v_mov_b32_e32 v140, 0
	v_mov_b32_e32 v141, 0
	v_mov_b32_e32 v142, 0
	v_mov_b32_e32 v143, 0
	v_mov_b32_e32 v254, 0
	v_mov_b32_e32 v144, 0
	v_mov_b32_e32 v145, 0
	v_mov_b32_e32 v146, 0
	v_mov_b32_e32 v147, 0
	v_mov_b32_e32 v148, 0
	v_mov_b32_e32 v149, 0
	v_mov_b32_e32 v150, 0
	v_mov_b32_e32 v151, 0
	v_mov_b32_e32 v152, 0
	v_mov_b32_e32 v153, 0
	v_mov_b32_e32 v154, 0
	v_mov_b32_e32 v155, 0
	v_mov_b32_e32 v156, 0
	v_mov_b32_e32 v157, 0
	v_mov_b32_e32 v158, 0
	v_mov_b32_e32 v159, 0
	v_mov_b32_e32 v255, 0
	ds_read_b128 v[168:171], v244 offset:0
	ds_read_b128 v[172:175], v245 offset:0
	ds_read_b128 v[176:179], v246 offset:0
	ds_read_b128 v[180:183], v247 offset:0
	ds_read_b128 v[184:187], v244 offset:4096
	ds_read_b128 v[188:191], v245 offset:4096
	ds_read_b128 v[232:235], v246 offset:4096
	ds_read_b128 v[240:243], v247 offset:4096
	v_mul_f32_e32 v252, v0, v200
	v_fmac_f32_e32 v254, v0, v0
	v_mul_f32_e32 v160, v32, v200
	v_fmac_f32_e32 v255, v32, v32
	s_waitcnt lgkmcnt(7)
	v_pk_fma_f32 v[128:129], v[252:253], v[168:169], v[128:129] op_sel_hi:[0,1,1]
	v_pk_fma_f32 v[144:145], v[160:161], v[168:169], v[144:145] op_sel_hi:[0,1,1]
	v_pk_fma_f32 v[130:131], v[252:253], v[170:171], v[130:131] op_sel_hi:[0,1,1]
	v_pk_fma_f32 v[146:147], v[160:161], v[170:171], v[146:147] op_sel_hi:[0,1,1]
	s_waitcnt lgkmcnt(6)
	v_pk_fma_f32 v[132:133], v[252:253], v[172:173], v[132:133] op_sel_hi:[0,1,1]
	v_pk_fma_f32 v[148:149], v[160:161], v[172:173], v[148:149] op_sel_hi:[0,1,1]
	v_pk_fma_f32 v[134:135], v[252:253], v[174:175], v[134:135] op_sel_hi:[0,1,1]
	v_pk_fma_f32 v[150:151], v[160:161], v[174:175], v[150:151] op_sel_hi:[0,1,1]
	s_waitcnt lgkmcnt(5)
	v_pk_fma_f32 v[136:137], v[252:253], v[176:177], v[136:137] op_sel_hi:[0,1,1]
	v_pk_fma_f32 v[152:153], v[160:161], v[176:177], v[152:153] op_sel_hi:[0,1,1]
	v_pk_fma_f32 v[138:139], v[252:253], v[178:179], v[138:139] op_sel_hi:[0,1,1]
	v_pk_fma_f32 v[154:155], v[160:161], v[178:179], v[154:155] op_sel_hi:[0,1,1]
	s_waitcnt lgkmcnt(4)
	v_pk_fma_f32 v[140:141], v[252:253], v[180:181], v[140:141] op_sel_hi:[0,1,1]
	v_pk_fma_f32 v[156:157], v[160:161], v[180:181], v[156:157] op_sel_hi:[0,1,1]
	v_pk_fma_f32 v[142:143], v[252:253], v[182:183], v[142:143] op_sel_hi:[0,1,1]
	v_pk_fma_f32 v[158:159], v[160:161], v[182:183], v[158:159] op_sel_hi:[0,1,1]
	ds_read_b128 v[168:171], v244 offset:8192
	ds_read_b128 v[172:175], v245 offset:8192
	ds_read_b128 v[176:179], v246 offset:8192
	ds_read_b128 v[180:183], v247 offset:8192
	v_mul_f32_e32 v252, v1, v201
	v_fmac_f32_e32 v254, v1, v1
	v_mul_f32_e32 v160, v33, v201
	v_fmac_f32_e32 v255, v33, v33
	s_waitcnt lgkmcnt(7)
	v_pk_fma_f32 v[128:129], v[252:253], v[184:185], v[128:129] op_sel_hi:[0,1,1]
	v_pk_fma_f32 v[144:145], v[160:161], v[184:185], v[144:145] op_sel_hi:[0,1,1]
	v_pk_fma_f32 v[130:131], v[252:253], v[186:187], v[130:131] op_sel_hi:[0,1,1]
	v_pk_fma_f32 v[146:147], v[160:161], v[186:187], v[146:147] op_sel_hi:[0,1,1]
	s_waitcnt lgkmcnt(6)
	v_pk_fma_f32 v[132:133], v[252:253], v[188:189], v[132:133] op_sel_hi:[0,1,1]
	v_pk_fma_f32 v[148:149], v[160:161], v[188:189], v[148:149] op_sel_hi:[0,1,1]
	v_pk_fma_f32 v[134:135], v[252:253], v[190:191], v[134:135] op_sel_hi:[0,1,1]
	v_pk_fma_f32 v[150:151], v[160:161], v[190:191], v[150:151] op_sel_hi:[0,1,1]
	s_waitcnt lgkmcnt(5)
	v_pk_fma_f32 v[136:137], v[252:253], v[232:233], v[136:137] op_sel_hi:[0,1,1]
	v_pk_fma_f32 v[152:153], v[160:161], v[232:233], v[152:153] op_sel_hi:[0,1,1]
	v_pk_fma_f32 v[138:139], v[252:253], v[234:235], v[138:139] op_sel_hi:[0,1,1]
	v_pk_fma_f32 v[154:155], v[160:161], v[234:235], v[154:155] op_sel_hi:[0,1,1]
	s_waitcnt lgkmcnt(4)
	v_pk_fma_f32 v[140:141], v[252:253], v[240:241], v[140:141] op_sel_hi:[0,1,1]
	v_pk_fma_f32 v[156:157], v[160:161], v[240:241], v[156:157] op_sel_hi:[0,1,1]
	v_pk_fma_f32 v[142:143], v[252:253], v[242:243], v[142:143] op_sel_hi:[0,1,1]
	v_pk_fma_f32 v[158:159], v[160:161], v[242:243], v[158:159] op_sel_hi:[0,1,1]
	ds_read_b128 v[184:187], v244 offset:12288
	ds_read_b128 v[188:191], v245 offset:12288
	ds_read_b128 v[232:235], v246 offset:12288
	ds_read_b128 v[240:243], v247 offset:12288
	v_mul_f32_e32 v252, v2, v202
	v_fmac_f32_e32 v254, v2, v2
	v_mul_f32_e32 v160, v34, v202
	v_fmac_f32_e32 v255, v34, v34
	s_waitcnt lgkmcnt(7)
	v_pk_fma_f32 v[128:129], v[252:253], v[168:169], v[128:129] op_sel_hi:[0,1,1]
	v_pk_fma_f32 v[144:145], v[160:161], v[168:169], v[144:145] op_sel_hi:[0,1,1]
	v_pk_fma_f32 v[130:131], v[252:253], v[170:171], v[130:131] op_sel_hi:[0,1,1]
	v_pk_fma_f32 v[146:147], v[160:161], v[170:171], v[146:147] op_sel_hi:[0,1,1]
	s_waitcnt lgkmcnt(6)
	v_pk_fma_f32 v[132:133], v[252:253], v[172:173], v[132:133] op_sel_hi:[0,1,1]
	v_pk_fma_f32 v[148:149], v[160:161], v[172:173], v[148:149] op_sel_hi:[0,1,1]
	v_pk_fma_f32 v[134:135], v[252:253], v[174:175], v[134:135] op_sel_hi:[0,1,1]
	v_pk_fma_f32 v[150:151], v[160:161], v[174:175], v[150:151] op_sel_hi:[0,1,1]
	s_waitcnt lgkmcnt(5)
	v_pk_fma_f32 v[136:137], v[252:253], v[176:177], v[136:137] op_sel_hi:[0,1,1]
	v_pk_fma_f32 v[152:153], v[160:161], v[176:177], v[152:153] op_sel_hi:[0,1,1]
	v_pk_fma_f32 v[138:139], v[252:253], v[178:179], v[138:139] op_sel_hi:[0,1,1]
	v_pk_fma_f32 v[154:155], v[160:161], v[178:179], v[154:155] op_sel_hi:[0,1,1]
	s_waitcnt lgkmcnt(4)
	v_pk_fma_f32 v[140:141], v[252:253], v[180:181], v[140:141] op_sel_hi:[0,1,1]
	v_pk_fma_f32 v[156:157], v[160:161], v[180:181], v[156:157] op_sel_hi:[0,1,1]
	v_pk_fma_f32 v[142:143], v[252:253], v[182:183], v[142:143] op_sel_hi:[0,1,1]
	v_pk_fma_f32 v[158:159], v[160:161], v[182:183], v[158:159] op_sel_hi:[0,1,1]
	ds_read_b128 v[168:171], v244 offset:16384
	ds_read_b128 v[172:175], v245 offset:16384
	ds_read_b128 v[176:179], v246 offset:16384
	ds_read_b128 v[180:183], v247 offset:16384
	v_mul_f32_e32 v252, v3, v203
	v_fmac_f32_e32 v254, v3, v3
	v_mul_f32_e32 v160, v35, v203
	v_fmac_f32_e32 v255, v35, v35
	s_waitcnt lgkmcnt(7)
	v_pk_fma_f32 v[128:129], v[252:253], v[184:185], v[128:129] op_sel_hi:[0,1,1]
	v_pk_fma_f32 v[144:145], v[160:161], v[184:185], v[144:145] op_sel_hi:[0,1,1]
	v_pk_fma_f32 v[130:131], v[252:253], v[186:187], v[130:131] op_sel_hi:[0,1,1]
	v_pk_fma_f32 v[146:147], v[160:161], v[186:187], v[146:147] op_sel_hi:[0,1,1]
	s_waitcnt lgkmcnt(6)
	v_pk_fma_f32 v[132:133], v[252:253], v[188:189], v[132:133] op_sel_hi:[0,1,1]
	v_pk_fma_f32 v[148:149], v[160:161], v[188:189], v[148:149] op_sel_hi:[0,1,1]
	v_pk_fma_f32 v[134:135], v[252:253], v[190:191], v[134:135] op_sel_hi:[0,1,1]
	v_pk_fma_f32 v[150:151], v[160:161], v[190:191], v[150:151] op_sel_hi:[0,1,1]
	s_waitcnt lgkmcnt(5)
	v_pk_fma_f32 v[136:137], v[252:253], v[232:233], v[136:137] op_sel_hi:[0,1,1]
	v_pk_fma_f32 v[152:153], v[160:161], v[232:233], v[152:153] op_sel_hi:[0,1,1]
	v_pk_fma_f32 v[138:139], v[252:253], v[234:235], v[138:139] op_sel_hi:[0,1,1]
	v_pk_fma_f32 v[154:155], v[160:161], v[234:235], v[154:155] op_sel_hi:[0,1,1]
	s_waitcnt lgkmcnt(4)
	v_pk_fma_f32 v[140:141], v[252:253], v[240:241], v[140:141] op_sel_hi:[0,1,1]
	v_pk_fma_f32 v[156:157], v[160:161], v[240:241], v[156:157] op_sel_hi:[0,1,1]
	v_pk_fma_f32 v[142:143], v[252:253], v[242:243], v[142:143] op_sel_hi:[0,1,1]
	v_pk_fma_f32 v[158:159], v[160:161], v[242:243], v[158:159] op_sel_hi:[0,1,1]
	ds_read_b128 v[184:187], v244 offset:20480
	ds_read_b128 v[188:191], v245 offset:20480
	ds_read_b128 v[232:235], v246 offset:20480
	ds_read_b128 v[240:243], v247 offset:20480
	v_mul_f32_e32 v252, v4, v204
	v_fmac_f32_e32 v254, v4, v4
	v_mul_f32_e32 v160, v36, v204
	v_fmac_f32_e32 v255, v36, v36
	s_waitcnt lgkmcnt(7)
	v_pk_fma_f32 v[128:129], v[252:253], v[168:169], v[128:129] op_sel_hi:[0,1,1]
	v_pk_fma_f32 v[144:145], v[160:161], v[168:169], v[144:145] op_sel_hi:[0,1,1]
	v_pk_fma_f32 v[130:131], v[252:253], v[170:171], v[130:131] op_sel_hi:[0,1,1]
	v_pk_fma_f32 v[146:147], v[160:161], v[170:171], v[146:147] op_sel_hi:[0,1,1]
	s_waitcnt lgkmcnt(6)
	v_pk_fma_f32 v[132:133], v[252:253], v[172:173], v[132:133] op_sel_hi:[0,1,1]
	v_pk_fma_f32 v[148:149], v[160:161], v[172:173], v[148:149] op_sel_hi:[0,1,1]
	v_pk_fma_f32 v[134:135], v[252:253], v[174:175], v[134:135] op_sel_hi:[0,1,1]
	v_pk_fma_f32 v[150:151], v[160:161], v[174:175], v[150:151] op_sel_hi:[0,1,1]
	s_waitcnt lgkmcnt(5)
	v_pk_fma_f32 v[136:137], v[252:253], v[176:177], v[136:137] op_sel_hi:[0,1,1]
	v_pk_fma_f32 v[152:153], v[160:161], v[176:177], v[152:153] op_sel_hi:[0,1,1]
	v_pk_fma_f32 v[138:139], v[252:253], v[178:179], v[138:139] op_sel_hi:[0,1,1]
	v_pk_fma_f32 v[154:155], v[160:161], v[178:179], v[154:155] op_sel_hi:[0,1,1]
	s_waitcnt lgkmcnt(4)
	v_pk_fma_f32 v[140:141], v[252:253], v[180:181], v[140:141] op_sel_hi:[0,1,1]
	v_pk_fma_f32 v[156:157], v[160:161], v[180:181], v[156:157] op_sel_hi:[0,1,1]
	v_pk_fma_f32 v[142:143], v[252:253], v[182:183], v[142:143] op_sel_hi:[0,1,1]
	v_pk_fma_f32 v[158:159], v[160:161], v[182:183], v[158:159] op_sel_hi:[0,1,1]
	ds_read_b128 v[168:171], v244 offset:24576
	ds_read_b128 v[172:175], v245 offset:24576
	ds_read_b128 v[176:179], v246 offset:24576
	ds_read_b128 v[180:183], v247 offset:24576
	v_mul_f32_e32 v252, v5, v205
	v_fmac_f32_e32 v254, v5, v5
	v_mul_f32_e32 v160, v37, v205
	v_fmac_f32_e32 v255, v37, v37
	s_waitcnt lgkmcnt(7)
	v_pk_fma_f32 v[128:129], v[252:253], v[184:185], v[128:129] op_sel_hi:[0,1,1]
	v_pk_fma_f32 v[144:145], v[160:161], v[184:185], v[144:145] op_sel_hi:[0,1,1]
	v_pk_fma_f32 v[130:131], v[252:253], v[186:187], v[130:131] op_sel_hi:[0,1,1]
	v_pk_fma_f32 v[146:147], v[160:161], v[186:187], v[146:147] op_sel_hi:[0,1,1]
	s_waitcnt lgkmcnt(6)
	v_pk_fma_f32 v[132:133], v[252:253], v[188:189], v[132:133] op_sel_hi:[0,1,1]
	v_pk_fma_f32 v[148:149], v[160:161], v[188:189], v[148:149] op_sel_hi:[0,1,1]
	v_pk_fma_f32 v[134:135], v[252:253], v[190:191], v[134:135] op_sel_hi:[0,1,1]
	v_pk_fma_f32 v[150:151], v[160:161], v[190:191], v[150:151] op_sel_hi:[0,1,1]
	s_waitcnt lgkmcnt(5)
	v_pk_fma_f32 v[136:137], v[252:253], v[232:233], v[136:137] op_sel_hi:[0,1,1]
	v_pk_fma_f32 v[152:153], v[160:161], v[232:233], v[152:153] op_sel_hi:[0,1,1]
	v_pk_fma_f32 v[138:139], v[252:253], v[234:235], v[138:139] op_sel_hi:[0,1,1]
	v_pk_fma_f32 v[154:155], v[160:161], v[234:235], v[154:155] op_sel_hi:[0,1,1]
	s_waitcnt lgkmcnt(4)
	v_pk_fma_f32 v[140:141], v[252:253], v[240:241], v[140:141] op_sel_hi:[0,1,1]
	v_pk_fma_f32 v[156:157], v[160:161], v[240:241], v[156:157] op_sel_hi:[0,1,1]
	v_pk_fma_f32 v[142:143], v[252:253], v[242:243], v[142:143] op_sel_hi:[0,1,1]
	v_pk_fma_f32 v[158:159], v[160:161], v[242:243], v[158:159] op_sel_hi:[0,1,1]
	ds_read_b128 v[184:187], v244 offset:28672
	ds_read_b128 v[188:191], v245 offset:28672
	ds_read_b128 v[232:235], v246 offset:28672
	ds_read_b128 v[240:243], v247 offset:28672
	v_mul_f32_e32 v252, v6, v206
	v_fmac_f32_e32 v254, v6, v6
	v_mul_f32_e32 v160, v38, v206
	v_fmac_f32_e32 v255, v38, v38
	s_waitcnt lgkmcnt(7)
	v_pk_fma_f32 v[128:129], v[252:253], v[168:169], v[128:129] op_sel_hi:[0,1,1]
	v_pk_fma_f32 v[144:145], v[160:161], v[168:169], v[144:145] op_sel_hi:[0,1,1]
	v_pk_fma_f32 v[130:131], v[252:253], v[170:171], v[130:131] op_sel_hi:[0,1,1]
	v_pk_fma_f32 v[146:147], v[160:161], v[170:171], v[146:147] op_sel_hi:[0,1,1]
	s_waitcnt lgkmcnt(6)
	v_pk_fma_f32 v[132:133], v[252:253], v[172:173], v[132:133] op_sel_hi:[0,1,1]
	v_pk_fma_f32 v[148:149], v[160:161], v[172:173], v[148:149] op_sel_hi:[0,1,1]
	v_pk_fma_f32 v[134:135], v[252:253], v[174:175], v[134:135] op_sel_hi:[0,1,1]
	v_pk_fma_f32 v[150:151], v[160:161], v[174:175], v[150:151] op_sel_hi:[0,1,1]
	s_waitcnt lgkmcnt(5)
	v_pk_fma_f32 v[136:137], v[252:253], v[176:177], v[136:137] op_sel_hi:[0,1,1]
	v_pk_fma_f32 v[152:153], v[160:161], v[176:177], v[152:153] op_sel_hi:[0,1,1]
	v_pk_fma_f32 v[138:139], v[252:253], v[178:179], v[138:139] op_sel_hi:[0,1,1]
	v_pk_fma_f32 v[154:155], v[160:161], v[178:179], v[154:155] op_sel_hi:[0,1,1]
	s_waitcnt lgkmcnt(4)
	v_pk_fma_f32 v[140:141], v[252:253], v[180:181], v[140:141] op_sel_hi:[0,1,1]
	v_pk_fma_f32 v[156:157], v[160:161], v[180:181], v[156:157] op_sel_hi:[0,1,1]
	v_pk_fma_f32 v[142:143], v[252:253], v[182:183], v[142:143] op_sel_hi:[0,1,1]
	v_pk_fma_f32 v[158:159], v[160:161], v[182:183], v[158:159] op_sel_hi:[0,1,1]
	ds_read_b128 v[168:171], v244 offset:32768
	ds_read_b128 v[172:175], v245 offset:32768
	ds_read_b128 v[176:179], v246 offset:32768
	ds_read_b128 v[180:183], v247 offset:32768
	v_mul_f32_e32 v252, v7, v207
	v_fmac_f32_e32 v254, v7, v7
	v_mul_f32_e32 v160, v39, v207
	v_fmac_f32_e32 v255, v39, v39
	s_waitcnt lgkmcnt(7)
	v_pk_fma_f32 v[128:129], v[252:253], v[184:185], v[128:129] op_sel_hi:[0,1,1]
	v_pk_fma_f32 v[144:145], v[160:161], v[184:185], v[144:145] op_sel_hi:[0,1,1]
	v_pk_fma_f32 v[130:131], v[252:253], v[186:187], v[130:131] op_sel_hi:[0,1,1]
	v_pk_fma_f32 v[146:147], v[160:161], v[186:187], v[146:147] op_sel_hi:[0,1,1]
	s_waitcnt lgkmcnt(6)
	v_pk_fma_f32 v[132:133], v[252:253], v[188:189], v[132:133] op_sel_hi:[0,1,1]
	v_pk_fma_f32 v[148:149], v[160:161], v[188:189], v[148:149] op_sel_hi:[0,1,1]
	v_pk_fma_f32 v[134:135], v[252:253], v[190:191], v[134:135] op_sel_hi:[0,1,1]
	v_pk_fma_f32 v[150:151], v[160:161], v[190:191], v[150:151] op_sel_hi:[0,1,1]
	s_waitcnt lgkmcnt(5)
	v_pk_fma_f32 v[136:137], v[252:253], v[232:233], v[136:137] op_sel_hi:[0,1,1]
	v_pk_fma_f32 v[152:153], v[160:161], v[232:233], v[152:153] op_sel_hi:[0,1,1]
	v_pk_fma_f32 v[138:139], v[252:253], v[234:235], v[138:139] op_sel_hi:[0,1,1]
	v_pk_fma_f32 v[154:155], v[160:161], v[234:235], v[154:155] op_sel_hi:[0,1,1]
	s_waitcnt lgkmcnt(4)
	v_pk_fma_f32 v[140:141], v[252:253], v[240:241], v[140:141] op_sel_hi:[0,1,1]
	v_pk_fma_f32 v[156:157], v[160:161], v[240:241], v[156:157] op_sel_hi:[0,1,1]
	v_pk_fma_f32 v[142:143], v[252:253], v[242:243], v[142:143] op_sel_hi:[0,1,1]
	v_pk_fma_f32 v[158:159], v[160:161], v[242:243], v[158:159] op_sel_hi:[0,1,1]
	ds_read_b128 v[184:187], v244 offset:36864
	ds_read_b128 v[188:191], v245 offset:36864
	ds_read_b128 v[232:235], v246 offset:36864
	ds_read_b128 v[240:243], v247 offset:36864
	v_mul_f32_e32 v252, v8, v208
	v_fmac_f32_e32 v254, v8, v8
	v_mul_f32_e32 v160, v40, v208
	v_fmac_f32_e32 v255, v40, v40
	s_waitcnt lgkmcnt(7)
	v_pk_fma_f32 v[128:129], v[252:253], v[168:169], v[128:129] op_sel_hi:[0,1,1]
	v_pk_fma_f32 v[144:145], v[160:161], v[168:169], v[144:145] op_sel_hi:[0,1,1]
	v_pk_fma_f32 v[130:131], v[252:253], v[170:171], v[130:131] op_sel_hi:[0,1,1]
	v_pk_fma_f32 v[146:147], v[160:161], v[170:171], v[146:147] op_sel_hi:[0,1,1]
	s_waitcnt lgkmcnt(6)
	v_pk_fma_f32 v[132:133], v[252:253], v[172:173], v[132:133] op_sel_hi:[0,1,1]
	v_pk_fma_f32 v[148:149], v[160:161], v[172:173], v[148:149] op_sel_hi:[0,1,1]
	v_pk_fma_f32 v[134:135], v[252:253], v[174:175], v[134:135] op_sel_hi:[0,1,1]
	v_pk_fma_f32 v[150:151], v[160:161], v[174:175], v[150:151] op_sel_hi:[0,1,1]
	s_waitcnt lgkmcnt(5)
	v_pk_fma_f32 v[136:137], v[252:253], v[176:177], v[136:137] op_sel_hi:[0,1,1]
	v_pk_fma_f32 v[152:153], v[160:161], v[176:177], v[152:153] op_sel_hi:[0,1,1]
	v_pk_fma_f32 v[138:139], v[252:253], v[178:179], v[138:139] op_sel_hi:[0,1,1]
	v_pk_fma_f32 v[154:155], v[160:161], v[178:179], v[154:155] op_sel_hi:[0,1,1]
	s_waitcnt lgkmcnt(4)
	v_pk_fma_f32 v[140:141], v[252:253], v[180:181], v[140:141] op_sel_hi:[0,1,1]
	v_pk_fma_f32 v[156:157], v[160:161], v[180:181], v[156:157] op_sel_hi:[0,1,1]
	v_pk_fma_f32 v[142:143], v[252:253], v[182:183], v[142:143] op_sel_hi:[0,1,1]
	v_pk_fma_f32 v[158:159], v[160:161], v[182:183], v[158:159] op_sel_hi:[0,1,1]
	ds_read_b128 v[168:171], v244 offset:40960
	ds_read_b128 v[172:175], v245 offset:40960
	ds_read_b128 v[176:179], v246 offset:40960
	ds_read_b128 v[180:183], v247 offset:40960
	v_mul_f32_e32 v252, v9, v209
	v_fmac_f32_e32 v254, v9, v9
	v_mul_f32_e32 v160, v41, v209
	v_fmac_f32_e32 v255, v41, v41
	s_waitcnt lgkmcnt(7)
	v_pk_fma_f32 v[128:129], v[252:253], v[184:185], v[128:129] op_sel_hi:[0,1,1]
	v_pk_fma_f32 v[144:145], v[160:161], v[184:185], v[144:145] op_sel_hi:[0,1,1]
	v_pk_fma_f32 v[130:131], v[252:253], v[186:187], v[130:131] op_sel_hi:[0,1,1]
	v_pk_fma_f32 v[146:147], v[160:161], v[186:187], v[146:147] op_sel_hi:[0,1,1]
	s_waitcnt lgkmcnt(6)
	v_pk_fma_f32 v[132:133], v[252:253], v[188:189], v[132:133] op_sel_hi:[0,1,1]
	v_pk_fma_f32 v[148:149], v[160:161], v[188:189], v[148:149] op_sel_hi:[0,1,1]
	v_pk_fma_f32 v[134:135], v[252:253], v[190:191], v[134:135] op_sel_hi:[0,1,1]
	v_pk_fma_f32 v[150:151], v[160:161], v[190:191], v[150:151] op_sel_hi:[0,1,1]
	s_waitcnt lgkmcnt(5)
	v_pk_fma_f32 v[136:137], v[252:253], v[232:233], v[136:137] op_sel_hi:[0,1,1]
	v_pk_fma_f32 v[152:153], v[160:161], v[232:233], v[152:153] op_sel_hi:[0,1,1]
	v_pk_fma_f32 v[138:139], v[252:253], v[234:235], v[138:139] op_sel_hi:[0,1,1]
	v_pk_fma_f32 v[154:155], v[160:161], v[234:235], v[154:155] op_sel_hi:[0,1,1]
	s_waitcnt lgkmcnt(4)
	v_pk_fma_f32 v[140:141], v[252:253], v[240:241], v[140:141] op_sel_hi:[0,1,1]
	v_pk_fma_f32 v[156:157], v[160:161], v[240:241], v[156:157] op_sel_hi:[0,1,1]
	v_pk_fma_f32 v[142:143], v[252:253], v[242:243], v[142:143] op_sel_hi:[0,1,1]
	v_pk_fma_f32 v[158:159], v[160:161], v[242:243], v[158:159] op_sel_hi:[0,1,1]
	ds_read_b128 v[184:187], v244 offset:45056
	ds_read_b128 v[188:191], v245 offset:45056
	ds_read_b128 v[232:235], v246 offset:45056
	ds_read_b128 v[240:243], v247 offset:45056
	v_mul_f32_e32 v252, v10, v210
	v_fmac_f32_e32 v254, v10, v10
	v_mul_f32_e32 v160, v42, v210
	v_fmac_f32_e32 v255, v42, v42
	s_waitcnt lgkmcnt(7)
	v_pk_fma_f32 v[128:129], v[252:253], v[168:169], v[128:129] op_sel_hi:[0,1,1]
	v_pk_fma_f32 v[144:145], v[160:161], v[168:169], v[144:145] op_sel_hi:[0,1,1]
	v_pk_fma_f32 v[130:131], v[252:253], v[170:171], v[130:131] op_sel_hi:[0,1,1]
	v_pk_fma_f32 v[146:147], v[160:161], v[170:171], v[146:147] op_sel_hi:[0,1,1]
	s_waitcnt lgkmcnt(6)
	v_pk_fma_f32 v[132:133], v[252:253], v[172:173], v[132:133] op_sel_hi:[0,1,1]
	v_pk_fma_f32 v[148:149], v[160:161], v[172:173], v[148:149] op_sel_hi:[0,1,1]
	v_pk_fma_f32 v[134:135], v[252:253], v[174:175], v[134:135] op_sel_hi:[0,1,1]
	v_pk_fma_f32 v[150:151], v[160:161], v[174:175], v[150:151] op_sel_hi:[0,1,1]
	s_waitcnt lgkmcnt(5)
	v_pk_fma_f32 v[136:137], v[252:253], v[176:177], v[136:137] op_sel_hi:[0,1,1]
	v_pk_fma_f32 v[152:153], v[160:161], v[176:177], v[152:153] op_sel_hi:[0,1,1]
	v_pk_fma_f32 v[138:139], v[252:253], v[178:179], v[138:139] op_sel_hi:[0,1,1]
	v_pk_fma_f32 v[154:155], v[160:161], v[178:179], v[154:155] op_sel_hi:[0,1,1]
	s_waitcnt lgkmcnt(4)
	v_pk_fma_f32 v[140:141], v[252:253], v[180:181], v[140:141] op_sel_hi:[0,1,1]
	v_pk_fma_f32 v[156:157], v[160:161], v[180:181], v[156:157] op_sel_hi:[0,1,1]
	v_pk_fma_f32 v[142:143], v[252:253], v[182:183], v[142:143] op_sel_hi:[0,1,1]
	v_pk_fma_f32 v[158:159], v[160:161], v[182:183], v[158:159] op_sel_hi:[0,1,1]
	ds_read_b128 v[168:171], v244 offset:49152
	ds_read_b128 v[172:175], v245 offset:49152
	ds_read_b128 v[176:179], v246 offset:49152
	ds_read_b128 v[180:183], v247 offset:49152
	v_mul_f32_e32 v252, v11, v211
	v_fmac_f32_e32 v254, v11, v11
	v_mul_f32_e32 v160, v43, v211
	v_fmac_f32_e32 v255, v43, v43
	s_waitcnt lgkmcnt(7)
	v_pk_fma_f32 v[128:129], v[252:253], v[184:185], v[128:129] op_sel_hi:[0,1,1]
	v_pk_fma_f32 v[144:145], v[160:161], v[184:185], v[144:145] op_sel_hi:[0,1,1]
	v_pk_fma_f32 v[130:131], v[252:253], v[186:187], v[130:131] op_sel_hi:[0,1,1]
	v_pk_fma_f32 v[146:147], v[160:161], v[186:187], v[146:147] op_sel_hi:[0,1,1]
	s_waitcnt lgkmcnt(6)
	v_pk_fma_f32 v[132:133], v[252:253], v[188:189], v[132:133] op_sel_hi:[0,1,1]
	v_pk_fma_f32 v[148:149], v[160:161], v[188:189], v[148:149] op_sel_hi:[0,1,1]
	v_pk_fma_f32 v[134:135], v[252:253], v[190:191], v[134:135] op_sel_hi:[0,1,1]
	v_pk_fma_f32 v[150:151], v[160:161], v[190:191], v[150:151] op_sel_hi:[0,1,1]
	s_waitcnt lgkmcnt(5)
	v_pk_fma_f32 v[136:137], v[252:253], v[232:233], v[136:137] op_sel_hi:[0,1,1]
	v_pk_fma_f32 v[152:153], v[160:161], v[232:233], v[152:153] op_sel_hi:[0,1,1]
	v_pk_fma_f32 v[138:139], v[252:253], v[234:235], v[138:139] op_sel_hi:[0,1,1]
	v_pk_fma_f32 v[154:155], v[160:161], v[234:235], v[154:155] op_sel_hi:[0,1,1]
	s_waitcnt lgkmcnt(4)
	v_pk_fma_f32 v[140:141], v[252:253], v[240:241], v[140:141] op_sel_hi:[0,1,1]
	v_pk_fma_f32 v[156:157], v[160:161], v[240:241], v[156:157] op_sel_hi:[0,1,1]
	v_pk_fma_f32 v[142:143], v[252:253], v[242:243], v[142:143] op_sel_hi:[0,1,1]
	v_pk_fma_f32 v[158:159], v[160:161], v[242:243], v[158:159] op_sel_hi:[0,1,1]
	ds_read_b128 v[184:187], v244 offset:53248
	ds_read_b128 v[188:191], v245 offset:53248
	ds_read_b128 v[232:235], v246 offset:53248
	ds_read_b128 v[240:243], v247 offset:53248
	v_mul_f32_e32 v252, v12, v212
	v_fmac_f32_e32 v254, v12, v12
	v_mul_f32_e32 v160, v44, v212
	v_fmac_f32_e32 v255, v44, v44
	s_waitcnt lgkmcnt(7)
	v_pk_fma_f32 v[128:129], v[252:253], v[168:169], v[128:129] op_sel_hi:[0,1,1]
	v_pk_fma_f32 v[144:145], v[160:161], v[168:169], v[144:145] op_sel_hi:[0,1,1]
	v_pk_fma_f32 v[130:131], v[252:253], v[170:171], v[130:131] op_sel_hi:[0,1,1]
	v_pk_fma_f32 v[146:147], v[160:161], v[170:171], v[146:147] op_sel_hi:[0,1,1]
	s_waitcnt lgkmcnt(6)
	v_pk_fma_f32 v[132:133], v[252:253], v[172:173], v[132:133] op_sel_hi:[0,1,1]
	v_pk_fma_f32 v[148:149], v[160:161], v[172:173], v[148:149] op_sel_hi:[0,1,1]
	v_pk_fma_f32 v[134:135], v[252:253], v[174:175], v[134:135] op_sel_hi:[0,1,1]
	v_pk_fma_f32 v[150:151], v[160:161], v[174:175], v[150:151] op_sel_hi:[0,1,1]
	s_waitcnt lgkmcnt(5)
	v_pk_fma_f32 v[136:137], v[252:253], v[176:177], v[136:137] op_sel_hi:[0,1,1]
	v_pk_fma_f32 v[152:153], v[160:161], v[176:177], v[152:153] op_sel_hi:[0,1,1]
	v_pk_fma_f32 v[138:139], v[252:253], v[178:179], v[138:139] op_sel_hi:[0,1,1]
	v_pk_fma_f32 v[154:155], v[160:161], v[178:179], v[154:155] op_sel_hi:[0,1,1]
	s_waitcnt lgkmcnt(4)
	v_pk_fma_f32 v[140:141], v[252:253], v[180:181], v[140:141] op_sel_hi:[0,1,1]
	v_pk_fma_f32 v[156:157], v[160:161], v[180:181], v[156:157] op_sel_hi:[0,1,1]
	v_pk_fma_f32 v[142:143], v[252:253], v[182:183], v[142:143] op_sel_hi:[0,1,1]
	v_pk_fma_f32 v[158:159], v[160:161], v[182:183], v[158:159] op_sel_hi:[0,1,1]
	ds_read_b128 v[168:171], v244 offset:57344
	ds_read_b128 v[172:175], v245 offset:57344
	ds_read_b128 v[176:179], v246 offset:57344
	ds_read_b128 v[180:183], v247 offset:57344
	v_mul_f32_e32 v252, v13, v213
	v_fmac_f32_e32 v254, v13, v13
	v_mul_f32_e32 v160, v45, v213
	v_fmac_f32_e32 v255, v45, v45
	s_waitcnt lgkmcnt(7)
	v_pk_fma_f32 v[128:129], v[252:253], v[184:185], v[128:129] op_sel_hi:[0,1,1]
	v_pk_fma_f32 v[144:145], v[160:161], v[184:185], v[144:145] op_sel_hi:[0,1,1]
	v_pk_fma_f32 v[130:131], v[252:253], v[186:187], v[130:131] op_sel_hi:[0,1,1]
	v_pk_fma_f32 v[146:147], v[160:161], v[186:187], v[146:147] op_sel_hi:[0,1,1]
	s_waitcnt lgkmcnt(6)
	v_pk_fma_f32 v[132:133], v[252:253], v[188:189], v[132:133] op_sel_hi:[0,1,1]
	v_pk_fma_f32 v[148:149], v[160:161], v[188:189], v[148:149] op_sel_hi:[0,1,1]
	v_pk_fma_f32 v[134:135], v[252:253], v[190:191], v[134:135] op_sel_hi:[0,1,1]
	v_pk_fma_f32 v[150:151], v[160:161], v[190:191], v[150:151] op_sel_hi:[0,1,1]
	s_waitcnt lgkmcnt(5)
	v_pk_fma_f32 v[136:137], v[252:253], v[232:233], v[136:137] op_sel_hi:[0,1,1]
	v_pk_fma_f32 v[152:153], v[160:161], v[232:233], v[152:153] op_sel_hi:[0,1,1]
	v_pk_fma_f32 v[138:139], v[252:253], v[234:235], v[138:139] op_sel_hi:[0,1,1]
	v_pk_fma_f32 v[154:155], v[160:161], v[234:235], v[154:155] op_sel_hi:[0,1,1]
	s_waitcnt lgkmcnt(4)
	v_pk_fma_f32 v[140:141], v[252:253], v[240:241], v[140:141] op_sel_hi:[0,1,1]
	v_pk_fma_f32 v[156:157], v[160:161], v[240:241], v[156:157] op_sel_hi:[0,1,1]
	v_pk_fma_f32 v[142:143], v[252:253], v[242:243], v[142:143] op_sel_hi:[0,1,1]
	v_pk_fma_f32 v[158:159], v[160:161], v[242:243], v[158:159] op_sel_hi:[0,1,1]
	ds_read_b128 v[184:187], v244 offset:61440
	ds_read_b128 v[188:191], v245 offset:61440
	ds_read_b128 v[232:235], v246 offset:61440
	ds_read_b128 v[240:243], v247 offset:61440
	v_mul_f32_e32 v252, v14, v214
	v_fmac_f32_e32 v254, v14, v14
	v_mul_f32_e32 v160, v46, v214
	v_fmac_f32_e32 v255, v46, v46
	s_waitcnt lgkmcnt(7)
	v_pk_fma_f32 v[128:129], v[252:253], v[168:169], v[128:129] op_sel_hi:[0,1,1]
	v_pk_fma_f32 v[144:145], v[160:161], v[168:169], v[144:145] op_sel_hi:[0,1,1]
	v_pk_fma_f32 v[130:131], v[252:253], v[170:171], v[130:131] op_sel_hi:[0,1,1]
	v_pk_fma_f32 v[146:147], v[160:161], v[170:171], v[146:147] op_sel_hi:[0,1,1]
	s_waitcnt lgkmcnt(6)
	v_pk_fma_f32 v[132:133], v[252:253], v[172:173], v[132:133] op_sel_hi:[0,1,1]
	v_pk_fma_f32 v[148:149], v[160:161], v[172:173], v[148:149] op_sel_hi:[0,1,1]
	v_pk_fma_f32 v[134:135], v[252:253], v[174:175], v[134:135] op_sel_hi:[0,1,1]
	v_pk_fma_f32 v[150:151], v[160:161], v[174:175], v[150:151] op_sel_hi:[0,1,1]
	s_waitcnt lgkmcnt(5)
	v_pk_fma_f32 v[136:137], v[252:253], v[176:177], v[136:137] op_sel_hi:[0,1,1]
	v_pk_fma_f32 v[152:153], v[160:161], v[176:177], v[152:153] op_sel_hi:[0,1,1]
	v_pk_fma_f32 v[138:139], v[252:253], v[178:179], v[138:139] op_sel_hi:[0,1,1]
	v_pk_fma_f32 v[154:155], v[160:161], v[178:179], v[154:155] op_sel_hi:[0,1,1]
	s_waitcnt lgkmcnt(4)
	v_pk_fma_f32 v[140:141], v[252:253], v[180:181], v[140:141] op_sel_hi:[0,1,1]
	v_pk_fma_f32 v[156:157], v[160:161], v[180:181], v[156:157] op_sel_hi:[0,1,1]
	v_pk_fma_f32 v[142:143], v[252:253], v[182:183], v[142:143] op_sel_hi:[0,1,1]
	v_pk_fma_f32 v[158:159], v[160:161], v[182:183], v[158:159] op_sel_hi:[0,1,1]
	ds_read_b128 v[168:171], v248 offset:0
	ds_read_b128 v[172:175], v249 offset:0
	ds_read_b128 v[176:179], v250 offset:0
	ds_read_b128 v[180:183], v251 offset:0
	v_mul_f32_e32 v252, v15, v215
	v_fmac_f32_e32 v254, v15, v15
	v_mul_f32_e32 v160, v47, v215
	v_fmac_f32_e32 v255, v47, v47
	s_waitcnt lgkmcnt(7)
	v_pk_fma_f32 v[128:129], v[252:253], v[184:185], v[128:129] op_sel_hi:[0,1,1]
	v_pk_fma_f32 v[144:145], v[160:161], v[184:185], v[144:145] op_sel_hi:[0,1,1]
	v_pk_fma_f32 v[130:131], v[252:253], v[186:187], v[130:131] op_sel_hi:[0,1,1]
	v_pk_fma_f32 v[146:147], v[160:161], v[186:187], v[146:147] op_sel_hi:[0,1,1]
	s_waitcnt lgkmcnt(6)
	v_pk_fma_f32 v[132:133], v[252:253], v[188:189], v[132:133] op_sel_hi:[0,1,1]
	v_pk_fma_f32 v[148:149], v[160:161], v[188:189], v[148:149] op_sel_hi:[0,1,1]
	v_pk_fma_f32 v[134:135], v[252:253], v[190:191], v[134:135] op_sel_hi:[0,1,1]
	v_pk_fma_f32 v[150:151], v[160:161], v[190:191], v[150:151] op_sel_hi:[0,1,1]
	s_waitcnt lgkmcnt(5)
	v_pk_fma_f32 v[136:137], v[252:253], v[232:233], v[136:137] op_sel_hi:[0,1,1]
	v_pk_fma_f32 v[152:153], v[160:161], v[232:233], v[152:153] op_sel_hi:[0,1,1]
	v_pk_fma_f32 v[138:139], v[252:253], v[234:235], v[138:139] op_sel_hi:[0,1,1]
	v_pk_fma_f32 v[154:155], v[160:161], v[234:235], v[154:155] op_sel_hi:[0,1,1]
	s_waitcnt lgkmcnt(4)
	v_pk_fma_f32 v[140:141], v[252:253], v[240:241], v[140:141] op_sel_hi:[0,1,1]
	v_pk_fma_f32 v[156:157], v[160:161], v[240:241], v[156:157] op_sel_hi:[0,1,1]
	v_pk_fma_f32 v[142:143], v[252:253], v[242:243], v[142:143] op_sel_hi:[0,1,1]
	v_pk_fma_f32 v[158:159], v[160:161], v[242:243], v[158:159] op_sel_hi:[0,1,1]
	ds_read_b128 v[184:187], v248 offset:4096
	ds_read_b128 v[188:191], v249 offset:4096
	ds_read_b128 v[232:235], v250 offset:4096
	ds_read_b128 v[240:243], v251 offset:4096
	v_mul_f32_e32 v252, v16, v216
	v_fmac_f32_e32 v254, v16, v16
	v_mul_f32_e32 v160, v48, v216
	v_fmac_f32_e32 v255, v48, v48
	s_waitcnt lgkmcnt(7)
	v_pk_fma_f32 v[128:129], v[252:253], v[168:169], v[128:129] op_sel_hi:[0,1,1]
	v_pk_fma_f32 v[144:145], v[160:161], v[168:169], v[144:145] op_sel_hi:[0,1,1]
	v_pk_fma_f32 v[130:131], v[252:253], v[170:171], v[130:131] op_sel_hi:[0,1,1]
	v_pk_fma_f32 v[146:147], v[160:161], v[170:171], v[146:147] op_sel_hi:[0,1,1]
	s_waitcnt lgkmcnt(6)
	v_pk_fma_f32 v[132:133], v[252:253], v[172:173], v[132:133] op_sel_hi:[0,1,1]
	v_pk_fma_f32 v[148:149], v[160:161], v[172:173], v[148:149] op_sel_hi:[0,1,1]
	v_pk_fma_f32 v[134:135], v[252:253], v[174:175], v[134:135] op_sel_hi:[0,1,1]
	v_pk_fma_f32 v[150:151], v[160:161], v[174:175], v[150:151] op_sel_hi:[0,1,1]
	s_waitcnt lgkmcnt(5)
	v_pk_fma_f32 v[136:137], v[252:253], v[176:177], v[136:137] op_sel_hi:[0,1,1]
	v_pk_fma_f32 v[152:153], v[160:161], v[176:177], v[152:153] op_sel_hi:[0,1,1]
	v_pk_fma_f32 v[138:139], v[252:253], v[178:179], v[138:139] op_sel_hi:[0,1,1]
	v_pk_fma_f32 v[154:155], v[160:161], v[178:179], v[154:155] op_sel_hi:[0,1,1]
	s_waitcnt lgkmcnt(4)
	v_pk_fma_f32 v[140:141], v[252:253], v[180:181], v[140:141] op_sel_hi:[0,1,1]
	v_pk_fma_f32 v[156:157], v[160:161], v[180:181], v[156:157] op_sel_hi:[0,1,1]
	v_pk_fma_f32 v[142:143], v[252:253], v[182:183], v[142:143] op_sel_hi:[0,1,1]
	v_pk_fma_f32 v[158:159], v[160:161], v[182:183], v[158:159] op_sel_hi:[0,1,1]
	ds_read_b128 v[168:171], v248 offset:8192
	ds_read_b128 v[172:175], v249 offset:8192
	ds_read_b128 v[176:179], v250 offset:8192
	ds_read_b128 v[180:183], v251 offset:8192
	v_mul_f32_e32 v252, v17, v217
	v_fmac_f32_e32 v254, v17, v17
	v_mul_f32_e32 v160, v49, v217
	v_fmac_f32_e32 v255, v49, v49
	s_waitcnt lgkmcnt(7)
	v_pk_fma_f32 v[128:129], v[252:253], v[184:185], v[128:129] op_sel_hi:[0,1,1]
	v_pk_fma_f32 v[144:145], v[160:161], v[184:185], v[144:145] op_sel_hi:[0,1,1]
	v_pk_fma_f32 v[130:131], v[252:253], v[186:187], v[130:131] op_sel_hi:[0,1,1]
	v_pk_fma_f32 v[146:147], v[160:161], v[186:187], v[146:147] op_sel_hi:[0,1,1]
	s_waitcnt lgkmcnt(6)
	v_pk_fma_f32 v[132:133], v[252:253], v[188:189], v[132:133] op_sel_hi:[0,1,1]
	v_pk_fma_f32 v[148:149], v[160:161], v[188:189], v[148:149] op_sel_hi:[0,1,1]
	v_pk_fma_f32 v[134:135], v[252:253], v[190:191], v[134:135] op_sel_hi:[0,1,1]
	v_pk_fma_f32 v[150:151], v[160:161], v[190:191], v[150:151] op_sel_hi:[0,1,1]
	s_waitcnt lgkmcnt(5)
	v_pk_fma_f32 v[136:137], v[252:253], v[232:233], v[136:137] op_sel_hi:[0,1,1]
	v_pk_fma_f32 v[152:153], v[160:161], v[232:233], v[152:153] op_sel_hi:[0,1,1]
	v_pk_fma_f32 v[138:139], v[252:253], v[234:235], v[138:139] op_sel_hi:[0,1,1]
	v_pk_fma_f32 v[154:155], v[160:161], v[234:235], v[154:155] op_sel_hi:[0,1,1]
	s_waitcnt lgkmcnt(4)
	v_pk_fma_f32 v[140:141], v[252:253], v[240:241], v[140:141] op_sel_hi:[0,1,1]
	v_pk_fma_f32 v[156:157], v[160:161], v[240:241], v[156:157] op_sel_hi:[0,1,1]
	v_pk_fma_f32 v[142:143], v[252:253], v[242:243], v[142:143] op_sel_hi:[0,1,1]
	v_pk_fma_f32 v[158:159], v[160:161], v[242:243], v[158:159] op_sel_hi:[0,1,1]
	ds_read_b128 v[184:187], v248 offset:12288
	ds_read_b128 v[188:191], v249 offset:12288
	ds_read_b128 v[232:235], v250 offset:12288
	ds_read_b128 v[240:243], v251 offset:12288
	v_mul_f32_e32 v252, v18, v218
	v_fmac_f32_e32 v254, v18, v18
	v_mul_f32_e32 v160, v50, v218
	v_fmac_f32_e32 v255, v50, v50
	s_waitcnt lgkmcnt(7)
	v_pk_fma_f32 v[128:129], v[252:253], v[168:169], v[128:129] op_sel_hi:[0,1,1]
	v_pk_fma_f32 v[144:145], v[160:161], v[168:169], v[144:145] op_sel_hi:[0,1,1]
	v_pk_fma_f32 v[130:131], v[252:253], v[170:171], v[130:131] op_sel_hi:[0,1,1]
	v_pk_fma_f32 v[146:147], v[160:161], v[170:171], v[146:147] op_sel_hi:[0,1,1]
	s_waitcnt lgkmcnt(6)
	v_pk_fma_f32 v[132:133], v[252:253], v[172:173], v[132:133] op_sel_hi:[0,1,1]
	v_pk_fma_f32 v[148:149], v[160:161], v[172:173], v[148:149] op_sel_hi:[0,1,1]
	v_pk_fma_f32 v[134:135], v[252:253], v[174:175], v[134:135] op_sel_hi:[0,1,1]
	v_pk_fma_f32 v[150:151], v[160:161], v[174:175], v[150:151] op_sel_hi:[0,1,1]
	s_waitcnt lgkmcnt(5)
	v_pk_fma_f32 v[136:137], v[252:253], v[176:177], v[136:137] op_sel_hi:[0,1,1]
	v_pk_fma_f32 v[152:153], v[160:161], v[176:177], v[152:153] op_sel_hi:[0,1,1]
	v_pk_fma_f32 v[138:139], v[252:253], v[178:179], v[138:139] op_sel_hi:[0,1,1]
	v_pk_fma_f32 v[154:155], v[160:161], v[178:179], v[154:155] op_sel_hi:[0,1,1]
	s_waitcnt lgkmcnt(4)
	v_pk_fma_f32 v[140:141], v[252:253], v[180:181], v[140:141] op_sel_hi:[0,1,1]
	v_pk_fma_f32 v[156:157], v[160:161], v[180:181], v[156:157] op_sel_hi:[0,1,1]
	v_pk_fma_f32 v[142:143], v[252:253], v[182:183], v[142:143] op_sel_hi:[0,1,1]
	v_pk_fma_f32 v[158:159], v[160:161], v[182:183], v[158:159] op_sel_hi:[0,1,1]
	ds_read_b128 v[168:171], v248 offset:16384
	ds_read_b128 v[172:175], v249 offset:16384
	ds_read_b128 v[176:179], v250 offset:16384
	ds_read_b128 v[180:183], v251 offset:16384
	v_mul_f32_e32 v252, v19, v219
	v_fmac_f32_e32 v254, v19, v19
	v_mul_f32_e32 v160, v51, v219
	v_fmac_f32_e32 v255, v51, v51
	s_waitcnt lgkmcnt(7)
	v_pk_fma_f32 v[128:129], v[252:253], v[184:185], v[128:129] op_sel_hi:[0,1,1]
	v_pk_fma_f32 v[144:145], v[160:161], v[184:185], v[144:145] op_sel_hi:[0,1,1]
	v_pk_fma_f32 v[130:131], v[252:253], v[186:187], v[130:131] op_sel_hi:[0,1,1]
	v_pk_fma_f32 v[146:147], v[160:161], v[186:187], v[146:147] op_sel_hi:[0,1,1]
	s_waitcnt lgkmcnt(6)
	v_pk_fma_f32 v[132:133], v[252:253], v[188:189], v[132:133] op_sel_hi:[0,1,1]
	v_pk_fma_f32 v[148:149], v[160:161], v[188:189], v[148:149] op_sel_hi:[0,1,1]
	v_pk_fma_f32 v[134:135], v[252:253], v[190:191], v[134:135] op_sel_hi:[0,1,1]
	v_pk_fma_f32 v[150:151], v[160:161], v[190:191], v[150:151] op_sel_hi:[0,1,1]
	s_waitcnt lgkmcnt(5)
	v_pk_fma_f32 v[136:137], v[252:253], v[232:233], v[136:137] op_sel_hi:[0,1,1]
	v_pk_fma_f32 v[152:153], v[160:161], v[232:233], v[152:153] op_sel_hi:[0,1,1]
	v_pk_fma_f32 v[138:139], v[252:253], v[234:235], v[138:139] op_sel_hi:[0,1,1]
	v_pk_fma_f32 v[154:155], v[160:161], v[234:235], v[154:155] op_sel_hi:[0,1,1]
	s_waitcnt lgkmcnt(4)
	v_pk_fma_f32 v[140:141], v[252:253], v[240:241], v[140:141] op_sel_hi:[0,1,1]
	v_pk_fma_f32 v[156:157], v[160:161], v[240:241], v[156:157] op_sel_hi:[0,1,1]
	v_pk_fma_f32 v[142:143], v[252:253], v[242:243], v[142:143] op_sel_hi:[0,1,1]
	v_pk_fma_f32 v[158:159], v[160:161], v[242:243], v[158:159] op_sel_hi:[0,1,1]
	ds_read_b128 v[184:187], v248 offset:20480
	ds_read_b128 v[188:191], v249 offset:20480
	ds_read_b128 v[232:235], v250 offset:20480
	ds_read_b128 v[240:243], v251 offset:20480
	v_mul_f32_e32 v252, v20, v220
	v_fmac_f32_e32 v254, v20, v20
	v_mul_f32_e32 v160, v52, v220
	v_fmac_f32_e32 v255, v52, v52
	s_waitcnt lgkmcnt(7)
	v_pk_fma_f32 v[128:129], v[252:253], v[168:169], v[128:129] op_sel_hi:[0,1,1]
	v_pk_fma_f32 v[144:145], v[160:161], v[168:169], v[144:145] op_sel_hi:[0,1,1]
	v_pk_fma_f32 v[130:131], v[252:253], v[170:171], v[130:131] op_sel_hi:[0,1,1]
	v_pk_fma_f32 v[146:147], v[160:161], v[170:171], v[146:147] op_sel_hi:[0,1,1]
	s_waitcnt lgkmcnt(6)
	v_pk_fma_f32 v[132:133], v[252:253], v[172:173], v[132:133] op_sel_hi:[0,1,1]
	v_pk_fma_f32 v[148:149], v[160:161], v[172:173], v[148:149] op_sel_hi:[0,1,1]
	v_pk_fma_f32 v[134:135], v[252:253], v[174:175], v[134:135] op_sel_hi:[0,1,1]
	v_pk_fma_f32 v[150:151], v[160:161], v[174:175], v[150:151] op_sel_hi:[0,1,1]
	s_waitcnt lgkmcnt(5)
	v_pk_fma_f32 v[136:137], v[252:253], v[176:177], v[136:137] op_sel_hi:[0,1,1]
	v_pk_fma_f32 v[152:153], v[160:161], v[176:177], v[152:153] op_sel_hi:[0,1,1]
	v_pk_fma_f32 v[138:139], v[252:253], v[178:179], v[138:139] op_sel_hi:[0,1,1]
	v_pk_fma_f32 v[154:155], v[160:161], v[178:179], v[154:155] op_sel_hi:[0,1,1]
	s_waitcnt lgkmcnt(4)
	v_pk_fma_f32 v[140:141], v[252:253], v[180:181], v[140:141] op_sel_hi:[0,1,1]
	v_pk_fma_f32 v[156:157], v[160:161], v[180:181], v[156:157] op_sel_hi:[0,1,1]
	v_pk_fma_f32 v[142:143], v[252:253], v[182:183], v[142:143] op_sel_hi:[0,1,1]
	v_pk_fma_f32 v[158:159], v[160:161], v[182:183], v[158:159] op_sel_hi:[0,1,1]
	ds_read_b128 v[168:171], v248 offset:24576
	ds_read_b128 v[172:175], v249 offset:24576
	ds_read_b128 v[176:179], v250 offset:24576
	ds_read_b128 v[180:183], v251 offset:24576
	v_mul_f32_e32 v252, v21, v221
	v_fmac_f32_e32 v254, v21, v21
	v_mul_f32_e32 v160, v53, v221
	v_fmac_f32_e32 v255, v53, v53
	s_waitcnt lgkmcnt(7)
	v_pk_fma_f32 v[128:129], v[252:253], v[184:185], v[128:129] op_sel_hi:[0,1,1]
	v_pk_fma_f32 v[144:145], v[160:161], v[184:185], v[144:145] op_sel_hi:[0,1,1]
	v_pk_fma_f32 v[130:131], v[252:253], v[186:187], v[130:131] op_sel_hi:[0,1,1]
	v_pk_fma_f32 v[146:147], v[160:161], v[186:187], v[146:147] op_sel_hi:[0,1,1]
	s_waitcnt lgkmcnt(6)
	v_pk_fma_f32 v[132:133], v[252:253], v[188:189], v[132:133] op_sel_hi:[0,1,1]
	v_pk_fma_f32 v[148:149], v[160:161], v[188:189], v[148:149] op_sel_hi:[0,1,1]
	v_pk_fma_f32 v[134:135], v[252:253], v[190:191], v[134:135] op_sel_hi:[0,1,1]
	v_pk_fma_f32 v[150:151], v[160:161], v[190:191], v[150:151] op_sel_hi:[0,1,1]
	s_waitcnt lgkmcnt(5)
	v_pk_fma_f32 v[136:137], v[252:253], v[232:233], v[136:137] op_sel_hi:[0,1,1]
	v_pk_fma_f32 v[152:153], v[160:161], v[232:233], v[152:153] op_sel_hi:[0,1,1]
	v_pk_fma_f32 v[138:139], v[252:253], v[234:235], v[138:139] op_sel_hi:[0,1,1]
	v_pk_fma_f32 v[154:155], v[160:161], v[234:235], v[154:155] op_sel_hi:[0,1,1]
	s_waitcnt lgkmcnt(4)
	v_pk_fma_f32 v[140:141], v[252:253], v[240:241], v[140:141] op_sel_hi:[0,1,1]
	v_pk_fma_f32 v[156:157], v[160:161], v[240:241], v[156:157] op_sel_hi:[0,1,1]
	v_pk_fma_f32 v[142:143], v[252:253], v[242:243], v[142:143] op_sel_hi:[0,1,1]
	v_pk_fma_f32 v[158:159], v[160:161], v[242:243], v[158:159] op_sel_hi:[0,1,1]
	ds_read_b128 v[184:187], v248 offset:28672
	ds_read_b128 v[188:191], v249 offset:28672
	ds_read_b128 v[232:235], v250 offset:28672
	ds_read_b128 v[240:243], v251 offset:28672
	v_mul_f32_e32 v252, v22, v222
	v_fmac_f32_e32 v254, v22, v22
	v_mul_f32_e32 v160, v54, v222
	v_fmac_f32_e32 v255, v54, v54
	s_waitcnt lgkmcnt(7)
	v_pk_fma_f32 v[128:129], v[252:253], v[168:169], v[128:129] op_sel_hi:[0,1,1]
	v_pk_fma_f32 v[144:145], v[160:161], v[168:169], v[144:145] op_sel_hi:[0,1,1]
	v_pk_fma_f32 v[130:131], v[252:253], v[170:171], v[130:131] op_sel_hi:[0,1,1]
	v_pk_fma_f32 v[146:147], v[160:161], v[170:171], v[146:147] op_sel_hi:[0,1,1]
	s_waitcnt lgkmcnt(6)
	v_pk_fma_f32 v[132:133], v[252:253], v[172:173], v[132:133] op_sel_hi:[0,1,1]
	v_pk_fma_f32 v[148:149], v[160:161], v[172:173], v[148:149] op_sel_hi:[0,1,1]
	v_pk_fma_f32 v[134:135], v[252:253], v[174:175], v[134:135] op_sel_hi:[0,1,1]
	v_pk_fma_f32 v[150:151], v[160:161], v[174:175], v[150:151] op_sel_hi:[0,1,1]
	s_waitcnt lgkmcnt(5)
	v_pk_fma_f32 v[136:137], v[252:253], v[176:177], v[136:137] op_sel_hi:[0,1,1]
	v_pk_fma_f32 v[152:153], v[160:161], v[176:177], v[152:153] op_sel_hi:[0,1,1]
	v_pk_fma_f32 v[138:139], v[252:253], v[178:179], v[138:139] op_sel_hi:[0,1,1]
	v_pk_fma_f32 v[154:155], v[160:161], v[178:179], v[154:155] op_sel_hi:[0,1,1]
	s_waitcnt lgkmcnt(4)
	v_pk_fma_f32 v[140:141], v[252:253], v[180:181], v[140:141] op_sel_hi:[0,1,1]
	v_pk_fma_f32 v[156:157], v[160:161], v[180:181], v[156:157] op_sel_hi:[0,1,1]
	v_pk_fma_f32 v[142:143], v[252:253], v[182:183], v[142:143] op_sel_hi:[0,1,1]
	v_pk_fma_f32 v[158:159], v[160:161], v[182:183], v[158:159] op_sel_hi:[0,1,1]
	ds_read_b128 v[168:171], v248 offset:32768
	ds_read_b128 v[172:175], v249 offset:32768
	ds_read_b128 v[176:179], v250 offset:32768
	ds_read_b128 v[180:183], v251 offset:32768
	v_mul_f32_e32 v252, v23, v223
	v_fmac_f32_e32 v254, v23, v23
	v_mul_f32_e32 v160, v55, v223
	v_fmac_f32_e32 v255, v55, v55
	s_waitcnt lgkmcnt(7)
	v_pk_fma_f32 v[128:129], v[252:253], v[184:185], v[128:129] op_sel_hi:[0,1,1]
	v_pk_fma_f32 v[144:145], v[160:161], v[184:185], v[144:145] op_sel_hi:[0,1,1]
	v_pk_fma_f32 v[130:131], v[252:253], v[186:187], v[130:131] op_sel_hi:[0,1,1]
	v_pk_fma_f32 v[146:147], v[160:161], v[186:187], v[146:147] op_sel_hi:[0,1,1]
	s_waitcnt lgkmcnt(6)
	v_pk_fma_f32 v[132:133], v[252:253], v[188:189], v[132:133] op_sel_hi:[0,1,1]
	v_pk_fma_f32 v[148:149], v[160:161], v[188:189], v[148:149] op_sel_hi:[0,1,1]
	v_pk_fma_f32 v[134:135], v[252:253], v[190:191], v[134:135] op_sel_hi:[0,1,1]
	v_pk_fma_f32 v[150:151], v[160:161], v[190:191], v[150:151] op_sel_hi:[0,1,1]
	s_waitcnt lgkmcnt(5)
	v_pk_fma_f32 v[136:137], v[252:253], v[232:233], v[136:137] op_sel_hi:[0,1,1]
	v_pk_fma_f32 v[152:153], v[160:161], v[232:233], v[152:153] op_sel_hi:[0,1,1]
	v_pk_fma_f32 v[138:139], v[252:253], v[234:235], v[138:139] op_sel_hi:[0,1,1]
	v_pk_fma_f32 v[154:155], v[160:161], v[234:235], v[154:155] op_sel_hi:[0,1,1]
	s_waitcnt lgkmcnt(4)
	v_pk_fma_f32 v[140:141], v[252:253], v[240:241], v[140:141] op_sel_hi:[0,1,1]
	v_pk_fma_f32 v[156:157], v[160:161], v[240:241], v[156:157] op_sel_hi:[0,1,1]
	v_pk_fma_f32 v[142:143], v[252:253], v[242:243], v[142:143] op_sel_hi:[0,1,1]
	v_pk_fma_f32 v[158:159], v[160:161], v[242:243], v[158:159] op_sel_hi:[0,1,1]
	ds_read_b128 v[184:187], v248 offset:36864
	ds_read_b128 v[188:191], v249 offset:36864
	ds_read_b128 v[232:235], v250 offset:36864
	ds_read_b128 v[240:243], v251 offset:36864
	v_mul_f32_e32 v252, v24, v224
	v_fmac_f32_e32 v254, v24, v24
	v_mul_f32_e32 v160, v56, v224
	v_fmac_f32_e32 v255, v56, v56
	s_waitcnt lgkmcnt(7)
	v_pk_fma_f32 v[128:129], v[252:253], v[168:169], v[128:129] op_sel_hi:[0,1,1]
	v_pk_fma_f32 v[144:145], v[160:161], v[168:169], v[144:145] op_sel_hi:[0,1,1]
	v_pk_fma_f32 v[130:131], v[252:253], v[170:171], v[130:131] op_sel_hi:[0,1,1]
	v_pk_fma_f32 v[146:147], v[160:161], v[170:171], v[146:147] op_sel_hi:[0,1,1]
	s_waitcnt lgkmcnt(6)
	v_pk_fma_f32 v[132:133], v[252:253], v[172:173], v[132:133] op_sel_hi:[0,1,1]
	v_pk_fma_f32 v[148:149], v[160:161], v[172:173], v[148:149] op_sel_hi:[0,1,1]
	v_pk_fma_f32 v[134:135], v[252:253], v[174:175], v[134:135] op_sel_hi:[0,1,1]
	v_pk_fma_f32 v[150:151], v[160:161], v[174:175], v[150:151] op_sel_hi:[0,1,1]
	s_waitcnt lgkmcnt(5)
	v_pk_fma_f32 v[136:137], v[252:253], v[176:177], v[136:137] op_sel_hi:[0,1,1]
	v_pk_fma_f32 v[152:153], v[160:161], v[176:177], v[152:153] op_sel_hi:[0,1,1]
	v_pk_fma_f32 v[138:139], v[252:253], v[178:179], v[138:139] op_sel_hi:[0,1,1]
	v_pk_fma_f32 v[154:155], v[160:161], v[178:179], v[154:155] op_sel_hi:[0,1,1]
	s_waitcnt lgkmcnt(4)
	v_pk_fma_f32 v[140:141], v[252:253], v[180:181], v[140:141] op_sel_hi:[0,1,1]
	v_pk_fma_f32 v[156:157], v[160:161], v[180:181], v[156:157] op_sel_hi:[0,1,1]
	v_pk_fma_f32 v[142:143], v[252:253], v[182:183], v[142:143] op_sel_hi:[0,1,1]
	v_pk_fma_f32 v[158:159], v[160:161], v[182:183], v[158:159] op_sel_hi:[0,1,1]
	ds_read_b128 v[168:171], v248 offset:40960
	ds_read_b128 v[172:175], v249 offset:40960
	ds_read_b128 v[176:179], v250 offset:40960
	ds_read_b128 v[180:183], v251 offset:40960
	v_mul_f32_e32 v252, v25, v225
	v_fmac_f32_e32 v254, v25, v25
	v_mul_f32_e32 v160, v57, v225
	v_fmac_f32_e32 v255, v57, v57
	s_waitcnt lgkmcnt(7)
	v_pk_fma_f32 v[128:129], v[252:253], v[184:185], v[128:129] op_sel_hi:[0,1,1]
	v_pk_fma_f32 v[144:145], v[160:161], v[184:185], v[144:145] op_sel_hi:[0,1,1]
	v_pk_fma_f32 v[130:131], v[252:253], v[186:187], v[130:131] op_sel_hi:[0,1,1]
	v_pk_fma_f32 v[146:147], v[160:161], v[186:187], v[146:147] op_sel_hi:[0,1,1]
	s_waitcnt lgkmcnt(6)
	v_pk_fma_f32 v[132:133], v[252:253], v[188:189], v[132:133] op_sel_hi:[0,1,1]
	v_pk_fma_f32 v[148:149], v[160:161], v[188:189], v[148:149] op_sel_hi:[0,1,1]
	v_pk_fma_f32 v[134:135], v[252:253], v[190:191], v[134:135] op_sel_hi:[0,1,1]
	v_pk_fma_f32 v[150:151], v[160:161], v[190:191], v[150:151] op_sel_hi:[0,1,1]
	s_waitcnt lgkmcnt(5)
	v_pk_fma_f32 v[136:137], v[252:253], v[232:233], v[136:137] op_sel_hi:[0,1,1]
	v_pk_fma_f32 v[152:153], v[160:161], v[232:233], v[152:153] op_sel_hi:[0,1,1]
	v_pk_fma_f32 v[138:139], v[252:253], v[234:235], v[138:139] op_sel_hi:[0,1,1]
	v_pk_fma_f32 v[154:155], v[160:161], v[234:235], v[154:155] op_sel_hi:[0,1,1]
	s_waitcnt lgkmcnt(4)
	v_pk_fma_f32 v[140:141], v[252:253], v[240:241], v[140:141] op_sel_hi:[0,1,1]
	v_pk_fma_f32 v[156:157], v[160:161], v[240:241], v[156:157] op_sel_hi:[0,1,1]
	v_pk_fma_f32 v[142:143], v[252:253], v[242:243], v[142:143] op_sel_hi:[0,1,1]
	v_pk_fma_f32 v[158:159], v[160:161], v[242:243], v[158:159] op_sel_hi:[0,1,1]
	ds_read_b128 v[184:187], v248 offset:45056
	ds_read_b128 v[188:191], v249 offset:45056
	ds_read_b128 v[232:235], v250 offset:45056
	ds_read_b128 v[240:243], v251 offset:45056
	v_mul_f32_e32 v252, v26, v226
	v_fmac_f32_e32 v254, v26, v26
	v_mul_f32_e32 v160, v58, v226
	v_fmac_f32_e32 v255, v58, v58
	s_waitcnt lgkmcnt(7)
	v_pk_fma_f32 v[128:129], v[252:253], v[168:169], v[128:129] op_sel_hi:[0,1,1]
	v_pk_fma_f32 v[144:145], v[160:161], v[168:169], v[144:145] op_sel_hi:[0,1,1]
	v_pk_fma_f32 v[130:131], v[252:253], v[170:171], v[130:131] op_sel_hi:[0,1,1]
	v_pk_fma_f32 v[146:147], v[160:161], v[170:171], v[146:147] op_sel_hi:[0,1,1]
	s_waitcnt lgkmcnt(6)
	v_pk_fma_f32 v[132:133], v[252:253], v[172:173], v[132:133] op_sel_hi:[0,1,1]
	v_pk_fma_f32 v[148:149], v[160:161], v[172:173], v[148:149] op_sel_hi:[0,1,1]
	v_pk_fma_f32 v[134:135], v[252:253], v[174:175], v[134:135] op_sel_hi:[0,1,1]
	v_pk_fma_f32 v[150:151], v[160:161], v[174:175], v[150:151] op_sel_hi:[0,1,1]
	s_waitcnt lgkmcnt(5)
	v_pk_fma_f32 v[136:137], v[252:253], v[176:177], v[136:137] op_sel_hi:[0,1,1]
	v_pk_fma_f32 v[152:153], v[160:161], v[176:177], v[152:153] op_sel_hi:[0,1,1]
	v_pk_fma_f32 v[138:139], v[252:253], v[178:179], v[138:139] op_sel_hi:[0,1,1]
	v_pk_fma_f32 v[154:155], v[160:161], v[178:179], v[154:155] op_sel_hi:[0,1,1]
	s_waitcnt lgkmcnt(4)
	v_pk_fma_f32 v[140:141], v[252:253], v[180:181], v[140:141] op_sel_hi:[0,1,1]
	v_pk_fma_f32 v[156:157], v[160:161], v[180:181], v[156:157] op_sel_hi:[0,1,1]
	v_pk_fma_f32 v[142:143], v[252:253], v[182:183], v[142:143] op_sel_hi:[0,1,1]
	v_pk_fma_f32 v[158:159], v[160:161], v[182:183], v[158:159] op_sel_hi:[0,1,1]
	ds_read_b128 v[168:171], v248 offset:49152
	ds_read_b128 v[172:175], v249 offset:49152
	ds_read_b128 v[176:179], v250 offset:49152
	ds_read_b128 v[180:183], v251 offset:49152
	v_mul_f32_e32 v252, v27, v227
	v_fmac_f32_e32 v254, v27, v27
	v_mul_f32_e32 v160, v59, v227
	v_fmac_f32_e32 v255, v59, v59
	s_waitcnt lgkmcnt(7)
	v_pk_fma_f32 v[128:129], v[252:253], v[184:185], v[128:129] op_sel_hi:[0,1,1]
	v_pk_fma_f32 v[144:145], v[160:161], v[184:185], v[144:145] op_sel_hi:[0,1,1]
	v_pk_fma_f32 v[130:131], v[252:253], v[186:187], v[130:131] op_sel_hi:[0,1,1]
	v_pk_fma_f32 v[146:147], v[160:161], v[186:187], v[146:147] op_sel_hi:[0,1,1]
	s_waitcnt lgkmcnt(6)
	v_pk_fma_f32 v[132:133], v[252:253], v[188:189], v[132:133] op_sel_hi:[0,1,1]
	v_pk_fma_f32 v[148:149], v[160:161], v[188:189], v[148:149] op_sel_hi:[0,1,1]
	v_pk_fma_f32 v[134:135], v[252:253], v[190:191], v[134:135] op_sel_hi:[0,1,1]
	v_pk_fma_f32 v[150:151], v[160:161], v[190:191], v[150:151] op_sel_hi:[0,1,1]
	s_waitcnt lgkmcnt(5)
	v_pk_fma_f32 v[136:137], v[252:253], v[232:233], v[136:137] op_sel_hi:[0,1,1]
	v_pk_fma_f32 v[152:153], v[160:161], v[232:233], v[152:153] op_sel_hi:[0,1,1]
	v_pk_fma_f32 v[138:139], v[252:253], v[234:235], v[138:139] op_sel_hi:[0,1,1]
	v_pk_fma_f32 v[154:155], v[160:161], v[234:235], v[154:155] op_sel_hi:[0,1,1]
	s_waitcnt lgkmcnt(4)
	v_pk_fma_f32 v[140:141], v[252:253], v[240:241], v[140:141] op_sel_hi:[0,1,1]
	v_pk_fma_f32 v[156:157], v[160:161], v[240:241], v[156:157] op_sel_hi:[0,1,1]
	v_pk_fma_f32 v[142:143], v[252:253], v[242:243], v[142:143] op_sel_hi:[0,1,1]
	v_pk_fma_f32 v[158:159], v[160:161], v[242:243], v[158:159] op_sel_hi:[0,1,1]
	ds_read_b128 v[184:187], v248 offset:53248
	ds_read_b128 v[188:191], v249 offset:53248
	ds_read_b128 v[232:235], v250 offset:53248
	ds_read_b128 v[240:243], v251 offset:53248
	v_mul_f32_e32 v252, v28, v228
	v_fmac_f32_e32 v254, v28, v28
	v_mul_f32_e32 v160, v60, v228
	v_fmac_f32_e32 v255, v60, v60
	s_waitcnt lgkmcnt(7)
	v_pk_fma_f32 v[128:129], v[252:253], v[168:169], v[128:129] op_sel_hi:[0,1,1]
	v_pk_fma_f32 v[144:145], v[160:161], v[168:169], v[144:145] op_sel_hi:[0,1,1]
	v_pk_fma_f32 v[130:131], v[252:253], v[170:171], v[130:131] op_sel_hi:[0,1,1]
	v_pk_fma_f32 v[146:147], v[160:161], v[170:171], v[146:147] op_sel_hi:[0,1,1]
	s_waitcnt lgkmcnt(6)
	v_pk_fma_f32 v[132:133], v[252:253], v[172:173], v[132:133] op_sel_hi:[0,1,1]
	v_pk_fma_f32 v[148:149], v[160:161], v[172:173], v[148:149] op_sel_hi:[0,1,1]
	v_pk_fma_f32 v[134:135], v[252:253], v[174:175], v[134:135] op_sel_hi:[0,1,1]
	v_pk_fma_f32 v[150:151], v[160:161], v[174:175], v[150:151] op_sel_hi:[0,1,1]
	s_waitcnt lgkmcnt(5)
	v_pk_fma_f32 v[136:137], v[252:253], v[176:177], v[136:137] op_sel_hi:[0,1,1]
	v_pk_fma_f32 v[152:153], v[160:161], v[176:177], v[152:153] op_sel_hi:[0,1,1]
	v_pk_fma_f32 v[138:139], v[252:253], v[178:179], v[138:139] op_sel_hi:[0,1,1]
	v_pk_fma_f32 v[154:155], v[160:161], v[178:179], v[154:155] op_sel_hi:[0,1,1]
	s_waitcnt lgkmcnt(4)
	v_pk_fma_f32 v[140:141], v[252:253], v[180:181], v[140:141] op_sel_hi:[0,1,1]
	v_pk_fma_f32 v[156:157], v[160:161], v[180:181], v[156:157] op_sel_hi:[0,1,1]
	v_pk_fma_f32 v[142:143], v[252:253], v[182:183], v[142:143] op_sel_hi:[0,1,1]
	v_pk_fma_f32 v[158:159], v[160:161], v[182:183], v[158:159] op_sel_hi:[0,1,1]
	ds_read_b128 v[168:171], v248 offset:57344
	ds_read_b128 v[172:175], v249 offset:57344
	ds_read_b128 v[176:179], v250 offset:57344
	ds_read_b128 v[180:183], v251 offset:57344
	v_mul_f32_e32 v252, v29, v229
	v_fmac_f32_e32 v254, v29, v29
	v_mul_f32_e32 v160, v61, v229
	v_fmac_f32_e32 v255, v61, v61
	s_waitcnt lgkmcnt(7)
	v_pk_fma_f32 v[128:129], v[252:253], v[184:185], v[128:129] op_sel_hi:[0,1,1]
	v_pk_fma_f32 v[144:145], v[160:161], v[184:185], v[144:145] op_sel_hi:[0,1,1]
	v_pk_fma_f32 v[130:131], v[252:253], v[186:187], v[130:131] op_sel_hi:[0,1,1]
	v_pk_fma_f32 v[146:147], v[160:161], v[186:187], v[146:147] op_sel_hi:[0,1,1]
	s_waitcnt lgkmcnt(6)
	v_pk_fma_f32 v[132:133], v[252:253], v[188:189], v[132:133] op_sel_hi:[0,1,1]
	v_pk_fma_f32 v[148:149], v[160:161], v[188:189], v[148:149] op_sel_hi:[0,1,1]
	v_pk_fma_f32 v[134:135], v[252:253], v[190:191], v[134:135] op_sel_hi:[0,1,1]
	v_pk_fma_f32 v[150:151], v[160:161], v[190:191], v[150:151] op_sel_hi:[0,1,1]
	s_waitcnt lgkmcnt(5)
	v_pk_fma_f32 v[136:137], v[252:253], v[232:233], v[136:137] op_sel_hi:[0,1,1]
	v_pk_fma_f32 v[152:153], v[160:161], v[232:233], v[152:153] op_sel_hi:[0,1,1]
	v_pk_fma_f32 v[138:139], v[252:253], v[234:235], v[138:139] op_sel_hi:[0,1,1]
	v_pk_fma_f32 v[154:155], v[160:161], v[234:235], v[154:155] op_sel_hi:[0,1,1]
	s_waitcnt lgkmcnt(4)
	v_pk_fma_f32 v[140:141], v[252:253], v[240:241], v[140:141] op_sel_hi:[0,1,1]
	v_pk_fma_f32 v[156:157], v[160:161], v[240:241], v[156:157] op_sel_hi:[0,1,1]
	v_pk_fma_f32 v[142:143], v[252:253], v[242:243], v[142:143] op_sel_hi:[0,1,1]
	v_pk_fma_f32 v[158:159], v[160:161], v[242:243], v[158:159] op_sel_hi:[0,1,1]
	ds_read_b128 v[184:187], v248 offset:61440
	ds_read_b128 v[188:191], v249 offset:61440
	ds_read_b128 v[232:235], v250 offset:61440
	ds_read_b128 v[240:243], v251 offset:61440
	v_mul_f32_e32 v252, v30, v230
	v_fmac_f32_e32 v254, v30, v30
	v_mul_f32_e32 v160, v62, v230
	v_fmac_f32_e32 v255, v62, v62
	s_waitcnt lgkmcnt(7)
	v_pk_fma_f32 v[128:129], v[252:253], v[168:169], v[128:129] op_sel_hi:[0,1,1]
	v_pk_fma_f32 v[144:145], v[160:161], v[168:169], v[144:145] op_sel_hi:[0,1,1]
	v_pk_fma_f32 v[130:131], v[252:253], v[170:171], v[130:131] op_sel_hi:[0,1,1]
	v_pk_fma_f32 v[146:147], v[160:161], v[170:171], v[146:147] op_sel_hi:[0,1,1]
	s_waitcnt lgkmcnt(6)
	v_pk_fma_f32 v[132:133], v[252:253], v[172:173], v[132:133] op_sel_hi:[0,1,1]
	v_pk_fma_f32 v[148:149], v[160:161], v[172:173], v[148:149] op_sel_hi:[0,1,1]
	v_pk_fma_f32 v[134:135], v[252:253], v[174:175], v[134:135] op_sel_hi:[0,1,1]
	v_pk_fma_f32 v[150:151], v[160:161], v[174:175], v[150:151] op_sel_hi:[0,1,1]
	s_waitcnt lgkmcnt(5)
	v_pk_fma_f32 v[136:137], v[252:253], v[176:177], v[136:137] op_sel_hi:[0,1,1]
	v_pk_fma_f32 v[152:153], v[160:161], v[176:177], v[152:153] op_sel_hi:[0,1,1]
	v_pk_fma_f32 v[138:139], v[252:253], v[178:179], v[138:139] op_sel_hi:[0,1,1]
	v_pk_fma_f32 v[154:155], v[160:161], v[178:179], v[154:155] op_sel_hi:[0,1,1]
	s_waitcnt lgkmcnt(4)
	v_pk_fma_f32 v[140:141], v[252:253], v[180:181], v[140:141] op_sel_hi:[0,1,1]
	v_pk_fma_f32 v[156:157], v[160:161], v[180:181], v[156:157] op_sel_hi:[0,1,1]
	v_pk_fma_f32 v[142:143], v[252:253], v[182:183], v[142:143] op_sel_hi:[0,1,1]
	v_pk_fma_f32 v[158:159], v[160:161], v[182:183], v[158:159] op_sel_hi:[0,1,1]
	v_mul_f32_e32 v252, v31, v231
	v_fmac_f32_e32 v254, v31, v31
	v_mul_f32_e32 v160, v63, v231
	v_fmac_f32_e32 v255, v63, v63
	s_waitcnt lgkmcnt(3)
	v_pk_fma_f32 v[128:129], v[252:253], v[184:185], v[128:129] op_sel_hi:[0,1,1]
	v_pk_fma_f32 v[144:145], v[160:161], v[184:185], v[144:145] op_sel_hi:[0,1,1]
	v_pk_fma_f32 v[130:131], v[252:253], v[186:187], v[130:131] op_sel_hi:[0,1,1]
	v_pk_fma_f32 v[146:147], v[160:161], v[186:187], v[146:147] op_sel_hi:[0,1,1]
	s_waitcnt lgkmcnt(2)
	v_pk_fma_f32 v[132:133], v[252:253], v[188:189], v[132:133] op_sel_hi:[0,1,1]
	v_pk_fma_f32 v[148:149], v[160:161], v[188:189], v[148:149] op_sel_hi:[0,1,1]
	v_pk_fma_f32 v[134:135], v[252:253], v[190:191], v[134:135] op_sel_hi:[0,1,1]
	v_pk_fma_f32 v[150:151], v[160:161], v[190:191], v[150:151] op_sel_hi:[0,1,1]
	s_waitcnt lgkmcnt(1)
	v_pk_fma_f32 v[136:137], v[252:253], v[232:233], v[136:137] op_sel_hi:[0,1,1]
	v_pk_fma_f32 v[152:153], v[160:161], v[232:233], v[152:153] op_sel_hi:[0,1,1]
	v_pk_fma_f32 v[138:139], v[252:253], v[234:235], v[138:139] op_sel_hi:[0,1,1]
	v_pk_fma_f32 v[154:155], v[160:161], v[234:235], v[154:155] op_sel_hi:[0,1,1]
	s_waitcnt lgkmcnt(0)
	v_pk_fma_f32 v[140:141], v[252:253], v[240:241], v[140:141] op_sel_hi:[0,1,1]
	v_pk_fma_f32 v[156:157], v[160:161], v[240:241], v[156:157] op_sel_hi:[0,1,1]
	v_pk_fma_f32 v[142:143], v[252:253], v[242:243], v[142:143] op_sel_hi:[0,1,1]
	v_pk_fma_f32 v[158:159], v[160:161], v[242:243], v[158:159] op_sel_hi:[0,1,1]
	v_xor_b32_e32 v162, 32, v197
	v_lshlrev_b32_e32 v162, 2, v162
	ds_bpermute_b32 v160, v162, v254
	ds_bpermute_b32 v161, v162, v255
	s_waitcnt lgkmcnt(0)
	v_add_f32_e32 v254, v254, v160
	v_add_f32_e32 v255, v255, v161
	v_xor_b32_e32 v162, 16, v197
	v_lshlrev_b32_e32 v162, 2, v162
	ds_bpermute_b32 v160, v162, v254
	ds_bpermute_b32 v161, v162, v255
	s_waitcnt lgkmcnt(0)
	v_add_f32_e32 v254, v254, v160
	v_add_f32_e32 v255, v255, v161
	v_xor_b32_e32 v162, 8, v197
	v_lshlrev_b32_e32 v162, 2, v162
	ds_bpermute_b32 v160, v162, v254
	ds_bpermute_b32 v161, v162, v255
	s_waitcnt lgkmcnt(0)
	v_add_f32_e32 v254, v254, v160
	v_add_f32_e32 v255, v255, v161
	v_xor_b32_e32 v162, 4, v197
	v_lshlrev_b32_e32 v162, 2, v162
	ds_bpermute_b32 v160, v162, v254
	ds_bpermute_b32 v161, v162, v255
	s_waitcnt lgkmcnt(0)
	v_add_f32_e32 v254, v254, v160
	v_add_f32_e32 v255, v255, v161
	v_xor_b32_e32 v162, 2, v197
	v_lshlrev_b32_e32 v162, 2, v162
	ds_bpermute_b32 v160, v162, v254
	ds_bpermute_b32 v161, v162, v255
	s_waitcnt lgkmcnt(0)
	v_add_f32_e32 v254, v254, v160
	v_add_f32_e32 v255, v255, v161
	v_xor_b32_e32 v162, 1, v197
	v_lshlrev_b32_e32 v162, 2, v162
	ds_bpermute_b32 v160, v162, v254
	ds_bpermute_b32 v161, v162, v255
	s_waitcnt lgkmcnt(0)
	v_add_f32_e32 v254, v254, v160
	v_add_f32_e32 v255, v255, v161
	v_mov_b32_e32 v160, 0x358637bd
	v_fma_f32 v254, v254, s20, v160
	v_fma_f32 v255, v255, s20, v160
	v_rsq_f32_e32 v254, v254
	v_rsq_f32_e32 v255, v255
	s_nop 0
	s_lshl_b32 s18, s16, 12
	s_add_u32 s22, s6, s18
	s_addc_u32 s23, s7, 0
	v_mul_f32_e32 v163, v0, v254
	v_mul_f32_e32 v165, v1, v254
	v_mul_f32_e32 v167, v2, v254
	v_mul_f32_e32 v199, v3, v254
	v_mul_f32_e32 v163, v163, v200
	v_mul_f32_e32 v165, v165, v201
	v_mul_f32_e32 v167, v167, v202
	v_mul_f32_e32 v199, v199, v203
	v_cvt_pk_bf16_f32 v192, v163, v165
	v_cvt_pk_bf16_f32 v193, v167, v199
	global_store_dwordx2 v164, v[192:193], s[22:23] offset:0
	v_mul_f32_e32 v163, v4, v254
	v_mul_f32_e32 v165, v5, v254
	v_mul_f32_e32 v167, v6, v254
	v_mul_f32_e32 v199, v7, v254
	v_mul_f32_e32 v163, v163, v204
	v_mul_f32_e32 v165, v165, v205
	v_mul_f32_e32 v167, v167, v206
	v_mul_f32_e32 v199, v199, v207
	v_cvt_pk_bf16_f32 v238, v163, v165
	v_cvt_pk_bf16_f32 v239, v167, v199
	global_store_dwordx2 v164, v[238:239], s[22:23] offset:512
	v_mul_f32_e32 v163, v8, v254
	v_mul_f32_e32 v165, v9, v254
	v_mul_f32_e32 v167, v10, v254
	v_mul_f32_e32 v199, v11, v254
	v_mul_f32_e32 v163, v163, v208
	v_mul_f32_e32 v165, v165, v209
	v_mul_f32_e32 v167, v167, v210
	v_mul_f32_e32 v199, v199, v211
	v_cvt_pk_bf16_f32 v192, v163, v165
	v_cvt_pk_bf16_f32 v193, v167, v199
	global_store_dwordx2 v164, v[192:193], s[22:23] offset:1024
	v_mul_f32_e32 v163, v12, v254
	v_mul_f32_e32 v165, v13, v254
	v_mul_f32_e32 v167, v14, v254
	v_mul_f32_e32 v199, v15, v254
	v_mul_f32_e32 v163, v163, v212
	v_mul_f32_e32 v165, v165, v213
	v_mul_f32_e32 v167, v167, v214
	v_mul_f32_e32 v199, v199, v215
	v_cvt_pk_bf16_f32 v238, v163, v165
	v_cvt_pk_bf16_f32 v239, v167, v199
	global_store_dwordx2 v164, v[238:239], s[22:23] offset:1536
	v_mul_f32_e32 v163, v16, v254
	v_mul_f32_e32 v165, v17, v254
	v_mul_f32_e32 v167, v18, v254
	v_mul_f32_e32 v199, v19, v254
	v_mul_f32_e32 v163, v163, v216
	v_mul_f32_e32 v165, v165, v217
	v_mul_f32_e32 v167, v167, v218
	v_mul_f32_e32 v199, v199, v219
	v_cvt_pk_bf16_f32 v192, v163, v165
	v_cvt_pk_bf16_f32 v193, v167, v199
	global_store_dwordx2 v164, v[192:193], s[22:23] offset:2048
	v_mul_f32_e32 v163, v20, v254
	v_mul_f32_e32 v165, v21, v254
	v_mul_f32_e32 v167, v22, v254
	v_mul_f32_e32 v199, v23, v254
	v_mul_f32_e32 v163, v163, v220
	v_mul_f32_e32 v165, v165, v221
	v_mul_f32_e32 v167, v167, v222
	v_mul_f32_e32 v199, v199, v223
	v_cvt_pk_bf16_f32 v238, v163, v165
	v_cvt_pk_bf16_f32 v239, v167, v199
	global_store_dwordx2 v164, v[238:239], s[22:23] offset:2560
	v_mul_f32_e32 v163, v24, v254
	v_mul_f32_e32 v165, v25, v254
	v_mul_f32_e32 v167, v26, v254
	v_mul_f32_e32 v199, v27, v254
	v_mul_f32_e32 v163, v163, v224
	v_mul_f32_e32 v165, v165, v225
	v_mul_f32_e32 v167, v167, v226
	v_mul_f32_e32 v199, v199, v227
	v_cvt_pk_bf16_f32 v192, v163, v165
	v_cvt_pk_bf16_f32 v193, v167, v199
	global_store_dwordx2 v164, v[192:193], s[22:23] offset:3072
	v_mul_f32_e32 v163, v28, v254
	v_mul_f32_e32 v165, v29, v254
	v_mul_f32_e32 v167, v30, v254
	v_mul_f32_e32 v199, v31, v254
	v_mul_f32_e32 v163, v163, v228
	v_mul_f32_e32 v165, v165, v229
	v_mul_f32_e32 v167, v167, v230
	v_mul_f32_e32 v199, v199, v231
	v_cvt_pk_bf16_f32 v238, v163, v165
	v_cvt_pk_bf16_f32 v239, v167, v199
	global_store_dwordx2 v164, v[238:239], s[22:23] offset:3584
	s_add_u32 s22, s22, 0x1000
	s_addc_u32 s23, s23, 0
	v_mul_f32_e32 v163, v32, v255
	v_mul_f32_e32 v165, v33, v255
	v_mul_f32_e32 v167, v34, v255
	v_mul_f32_e32 v199, v35, v255
	v_mul_f32_e32 v163, v163, v200
	v_mul_f32_e32 v165, v165, v201
	v_mul_f32_e32 v167, v167, v202
	v_mul_f32_e32 v199, v199, v203
	v_cvt_pk_bf16_f32 v192, v163, v165
	v_cvt_pk_bf16_f32 v193, v167, v199
	global_store_dwordx2 v164, v[192:193], s[22:23] offset:0
	v_mul_f32_e32 v163, v36, v255
	v_mul_f32_e32 v165, v37, v255
	v_mul_f32_e32 v167, v38, v255
	v_mul_f32_e32 v199, v39, v255
	v_mul_f32_e32 v163, v163, v204
	v_mul_f32_e32 v165, v165, v205
	v_mul_f32_e32 v167, v167, v206
	v_mul_f32_e32 v199, v199, v207
	v_cvt_pk_bf16_f32 v238, v163, v165
	v_cvt_pk_bf16_f32 v239, v167, v199
	global_store_dwordx2 v164, v[238:239], s[22:23] offset:512
	v_mul_f32_e32 v163, v40, v255
	v_mul_f32_e32 v165, v41, v255
	v_mul_f32_e32 v167, v42, v255
	v_mul_f32_e32 v199, v43, v255
	v_mul_f32_e32 v163, v163, v208
	v_mul_f32_e32 v165, v165, v209
	v_mul_f32_e32 v167, v167, v210
	v_mul_f32_e32 v199, v199, v211
	v_cvt_pk_bf16_f32 v192, v163, v165
	v_cvt_pk_bf16_f32 v193, v167, v199
	global_store_dwordx2 v164, v[192:193], s[22:23] offset:1024
	v_mul_f32_e32 v163, v44, v255
	v_mul_f32_e32 v165, v45, v255
	v_mul_f32_e32 v167, v46, v255
	v_mul_f32_e32 v199, v47, v255
	v_mul_f32_e32 v163, v163, v212
	v_mul_f32_e32 v165, v165, v213
	v_mul_f32_e32 v167, v167, v214
	v_mul_f32_e32 v199, v199, v215
	v_cvt_pk_bf16_f32 v238, v163, v165
	v_cvt_pk_bf16_f32 v239, v167, v199
	global_store_dwordx2 v164, v[238:239], s[22:23] offset:1536
	v_mul_f32_e32 v163, v48, v255
	v_mul_f32_e32 v165, v49, v255
	v_mul_f32_e32 v167, v50, v255
	v_mul_f32_e32 v199, v51, v255
	v_mul_f32_e32 v163, v163, v216
	v_mul_f32_e32 v165, v165, v217
	v_mul_f32_e32 v167, v167, v218
	v_mul_f32_e32 v199, v199, v219
	v_cvt_pk_bf16_f32 v192, v163, v165
	v_cvt_pk_bf16_f32 v193, v167, v199
	global_store_dwordx2 v164, v[192:193], s[22:23] offset:2048
	v_mul_f32_e32 v163, v52, v255
	v_mul_f32_e32 v165, v53, v255
	v_mul_f32_e32 v167, v54, v255
	v_mul_f32_e32 v199, v55, v255
	v_mul_f32_e32 v163, v163, v220
	v_mul_f32_e32 v165, v165, v221
	v_mul_f32_e32 v167, v167, v222
	v_mul_f32_e32 v199, v199, v223
	v_cvt_pk_bf16_f32 v238, v163, v165
	v_cvt_pk_bf16_f32 v239, v167, v199
	global_store_dwordx2 v164, v[238:239], s[22:23] offset:2560
	v_mul_f32_e32 v163, v56, v255
	v_mul_f32_e32 v165, v57, v255
	v_mul_f32_e32 v167, v58, v255
	v_mul_f32_e32 v199, v59, v255
	v_mul_f32_e32 v163, v163, v224
	v_mul_f32_e32 v165, v165, v225
	v_mul_f32_e32 v167, v167, v226
	v_mul_f32_e32 v199, v199, v227
	v_cvt_pk_bf16_f32 v192, v163, v165
	v_cvt_pk_bf16_f32 v193, v167, v199
	global_store_dwordx2 v164, v[192:193], s[22:23] offset:3072
	v_mul_f32_e32 v163, v60, v255
	v_mul_f32_e32 v165, v61, v255
	v_mul_f32_e32 v167, v62, v255
	v_mul_f32_e32 v199, v63, v255
	v_mul_f32_e32 v163, v163, v228
	v_mul_f32_e32 v165, v165, v229
	v_mul_f32_e32 v167, v167, v230
	v_mul_f32_e32 v199, v199, v231
	v_cvt_pk_bf16_f32 v238, v163, v165
	v_cvt_pk_bf16_f32 v239, v167, v199
	global_store_dwordx2 v164, v[238:239], s[22:23] offset:3584
	v_xor_b32_e32 v162, 32, v197
	v_lshlrev_b32_e32 v162, 2, v162
	v_cndmask_b32_e64 v163, v144, v128, s[24:25]
	v_cndmask_b32_e64 v128, v128, v144, s[24:25]
	ds_bpermute_b32 v144, v162, v163
	v_cndmask_b32_e64 v165, v145, v129, s[24:25]
	v_cndmask_b32_e64 v129, v129, v145, s[24:25]
	ds_bpermute_b32 v145, v162, v165
	v_cndmask_b32_e64 v167, v146, v130, s[24:25]
	v_cndmask_b32_e64 v130, v130, v146, s[24:25]
	ds_bpermute_b32 v146, v162, v167
	v_cndmask_b32_e64 v199, v147, v131, s[24:25]
	v_cndmask_b32_e64 v131, v131, v147, s[24:25]
	ds_bpermute_b32 v147, v162, v199
	v_cndmask_b32_e64 v163, v148, v132, s[24:25]
	v_cndmask_b32_e64 v132, v132, v148, s[24:25]
	ds_bpermute_b32 v148, v162, v163
	v_cndmask_b32_e64 v165, v149, v133, s[24:25]
	v_cndmask_b32_e64 v133, v133, v149, s[24:25]
	ds_bpermute_b32 v149, v162, v165
	v_cndmask_b32_e64 v167, v150, v134, s[24:25]
	v_cndmask_b32_e64 v134, v134, v150, s[24:25]
	ds_bpermute_b32 v150, v162, v167
	v_cndmask_b32_e64 v199, v151, v135, s[24:25]
	v_cndmask_b32_e64 v135, v135, v151, s[24:25]
	ds_bpermute_b32 v151, v162, v199
	s_waitcnt lgkmcnt(0)
	v_add_f32_e32 v128, v128, v144
	v_add_f32_e32 v129, v129, v145
	v_add_f32_e32 v130, v130, v146
	v_add_f32_e32 v131, v131, v147
	v_add_f32_e32 v132, v132, v148
	v_add_f32_e32 v133, v133, v149
	v_add_f32_e32 v134, v134, v150
	v_add_f32_e32 v135, v135, v151
	v_cndmask_b32_e64 v163, v152, v136, s[24:25]
	v_cndmask_b32_e64 v136, v136, v152, s[24:25]
	ds_bpermute_b32 v152, v162, v163
	v_cndmask_b32_e64 v165, v153, v137, s[24:25]
	v_cndmask_b32_e64 v137, v137, v153, s[24:25]
	ds_bpermute_b32 v153, v162, v165
	v_cndmask_b32_e64 v167, v154, v138, s[24:25]
	v_cndmask_b32_e64 v138, v138, v154, s[24:25]
	ds_bpermute_b32 v154, v162, v167
	v_cndmask_b32_e64 v199, v155, v139, s[24:25]
	v_cndmask_b32_e64 v139, v139, v155, s[24:25]
	ds_bpermute_b32 v155, v162, v199
	v_cndmask_b32_e64 v163, v156, v140, s[24:25]
	v_cndmask_b32_e64 v140, v140, v156, s[24:25]
	ds_bpermute_b32 v156, v162, v163
	v_cndmask_b32_e64 v165, v157, v141, s[24:25]
	v_cndmask_b32_e64 v141, v141, v157, s[24:25]
	ds_bpermute_b32 v157, v162, v165
	v_cndmask_b32_e64 v167, v158, v142, s[24:25]
	v_cndmask_b32_e64 v142, v142, v158, s[24:25]
	ds_bpermute_b32 v158, v162, v167
	v_cndmask_b32_e64 v199, v159, v143, s[24:25]
	v_cndmask_b32_e64 v143, v143, v159, s[24:25]
	ds_bpermute_b32 v159, v162, v199
	s_waitcnt lgkmcnt(0)
	v_add_f32_e32 v136, v136, v152
	v_add_f32_e32 v137, v137, v153
	v_add_f32_e32 v138, v138, v154
	v_add_f32_e32 v139, v139, v155
	v_add_f32_e32 v140, v140, v156
	v_add_f32_e32 v141, v141, v157
	v_add_f32_e32 v142, v142, v158
	v_add_f32_e32 v143, v143, v159
	v_xor_b32_e32 v162, 16, v197
	v_lshlrev_b32_e32 v162, 2, v162
	v_cndmask_b32_e64 v163, v136, v128, s[26:27]
	v_cndmask_b32_e64 v128, v128, v136, s[26:27]
	ds_bpermute_b32 v136, v162, v163
	v_cndmask_b32_e64 v165, v137, v129, s[26:27]
	v_cndmask_b32_e64 v129, v129, v137, s[26:27]
	ds_bpermute_b32 v137, v162, v165
	v_cndmask_b32_e64 v167, v138, v130, s[26:27]
	v_cndmask_b32_e64 v130, v130, v138, s[26:27]
	ds_bpermute_b32 v138, v162, v167
	v_cndmask_b32_e64 v199, v139, v131, s[26:27]
	v_cndmask_b32_e64 v131, v131, v139, s[26:27]
	ds_bpermute_b32 v139, v162, v199
	v_cndmask_b32_e64 v163, v140, v132, s[26:27]
	v_cndmask_b32_e64 v132, v132, v140, s[26:27]
	ds_bpermute_b32 v140, v162, v163
	v_cndmask_b32_e64 v165, v141, v133, s[26:27]
	v_cndmask_b32_e64 v133, v133, v141, s[26:27]
	ds_bpermute_b32 v141, v162, v165
	v_cndmask_b32_e64 v167, v142, v134, s[26:27]
	v_cndmask_b32_e64 v134, v134, v142, s[26:27]
	ds_bpermute_b32 v142, v162, v167
	v_cndmask_b32_e64 v199, v143, v135, s[26:27]
	v_cndmask_b32_e64 v135, v135, v143, s[26:27]
	ds_bpermute_b32 v143, v162, v199
	s_waitcnt lgkmcnt(0)
	v_add_f32_e32 v128, v128, v136
	v_add_f32_e32 v129, v129, v137
	v_add_f32_e32 v130, v130, v138
	v_add_f32_e32 v131, v131, v139
	v_add_f32_e32 v132, v132, v140
	v_add_f32_e32 v133, v133, v141
	v_add_f32_e32 v134, v134, v142
	v_add_f32_e32 v135, v135, v143
	v_xor_b32_e32 v162, 8, v197
	v_lshlrev_b32_e32 v162, 2, v162
	v_cndmask_b32_e64 v163, v132, v128, s[28:29]
	v_cndmask_b32_e64 v128, v128, v132, s[28:29]
	ds_bpermute_b32 v132, v162, v163
	v_cndmask_b32_e64 v165, v133, v129, s[28:29]
	v_cndmask_b32_e64 v129, v129, v133, s[28:29]
	ds_bpermute_b32 v133, v162, v165
	v_cndmask_b32_e64 v167, v134, v130, s[28:29]
	v_cndmask_b32_e64 v130, v130, v134, s[28:29]
	ds_bpermute_b32 v134, v162, v167
	v_cndmask_b32_e64 v199, v135, v131, s[28:29]
	v_cndmask_b32_e64 v131, v131, v135, s[28:29]
	ds_bpermute_b32 v135, v162, v199
	s_waitcnt lgkmcnt(0)
	v_add_f32_e32 v128, v128, v132
	v_add_f32_e32 v129, v129, v133
	v_add_f32_e32 v130, v130, v134
	v_add_f32_e32 v131, v131, v135
	v_xor_b32_e32 v162, 4, v197
	v_lshlrev_b32_e32 v162, 2, v162
	v_cndmask_b32_e64 v163, v130, v128, s[30:31]
	v_cndmask_b32_e64 v128, v128, v130, s[30:31]
	ds_bpermute_b32 v130, v162, v163
	v_cndmask_b32_e64 v165, v131, v129, s[30:31]
	v_cndmask_b32_e64 v129, v129, v131, s[30:31]
	ds_bpermute_b32 v131, v162, v165
	s_waitcnt lgkmcnt(0)
	v_add_f32_e32 v128, v128, v130
	v_add_f32_e32 v129, v129, v131
	v_xor_b32_e32 v162, 2, v197
	v_lshlrev_b32_e32 v162, 2, v162
	v_cndmask_b32_e64 v163, v129, v128, s[34:35]
	v_cndmask_b32_e64 v128, v128, v129, s[34:35]
	ds_bpermute_b32 v129, v162, v163
	s_waitcnt lgkmcnt(0)
	v_add_f32_e32 v128, v128, v129
	v_xor_b32_e32 v162, 1, v197
	v_lshlrev_b32_e32 v162, 2, v162
	ds_bpermute_b32 v160, v162, v128
	s_waitcnt lgkmcnt(0)
	v_add_f32_e32 v128, v128, v160
	v_cndmask_b32_e64 v160, v254, v255, s[24:25]
	v_mul_f32_e32 v128, v128, v160
	v_mul_f32_e32 v163, 0xbfb8aa3b, v128
	v_exp_f32_e32 v163, v163
	v_add_f32_e32 v167, v128, v195
	v_add_f32_e32 v163, 1.0, v163
	v_and_b32_e32 v199, 0x7fffffff, v167
	v_mul_f32_e32 v199, 0xbfb8aa3b, v199
	v_exp_f32_e32 v199, v199
	v_rcp_f32_e32 v163, v163
	v_add_f32_e32 v160, 1.0, v199
	v_log_f32_e32 v160, v160
	v_mul_f32_e32 v161, v199, v199
	v_mul_f32_e32 v160, 0x3f317218, v160
	v_mul_f32_e32 v162, v161, v199
	v_fma_f32 v161, v161, -0.5, v199
	v_mov_b32_e32 v165, 0x3eaaaaab
	v_fmac_f32_e32 v161, v162, v165
	v_cmp_gt_f32_e32 vcc, 0x3c800000, v199
	v_max_f32_e32 v167, 0, v167
	s_nop 0
	v_cndmask_b32_e32 v160, v160, v161, vcc
	v_add_f32_e32 v167, v167, v160
	v_mul_f32_e64 v165, -v237, v167
	v_bfe_u32 v162, v197, 1, 4
	v_cmp_gt_u32_e32 vcc, 8, v162
	v_and_b32_e32 v162, 7, v162
	s_lshr_b32 s18, s16, 11
	s_lshl_b32 s18, s18, 3
	v_add_u32_e32 v162, s18, v162
	v_lshlrev_b32_e32 v162, 13, v162
	s_and_b32 s18, s16, 2047
	v_lshrrev_b32_e32 v161, 5, v197
	v_add_u32_e32 v161, s18, v161
	v_lshl_add_u32 v162, v161, 2, v162
	v_cndmask_b32_e32 v160, v165, v163, vcc
	v_and_b32_e32 v161, 1, v197
	v_cmp_eq_u32_e64 s[22:23], 0, v161
	s_nop 1
	s_and_b64 s[0:1], s[22:23], vcc
	s_andn2_b64 s[2:3], s[22:23], vcc
	s_mov_b64 s[22:23], exec
	s_mov_b64 exec, s[0:1]
	global_store_dword v162, v160, s[12:13]
	s_mov_b64 exec, s[2:3]
	global_store_dword v162, v160, s[14:15]
	s_mov_b64 exec, s[22:23]
	s_add_u32 s16, s16, 2
	s_add_u32 s17, s17, 1
	s_cmp_lt_u32 s17, 4
	s_cbranch_scc1 .Lp0_loop
	v_lshrrev_b32_e32 v136, 4, v198
	v_lshrrev_b32_e32 v145, 3, v198
	v_lshlrev_b32_e32 v144, 3, v198
	v_readlane_b32 s72, v236, 22
	v_readlane_b32 s73, v236, 23
	v_readlane_b32 s74, v236, 24
	v_readlane_b32 s75, v236, 25
	v_readlane_b32 s76, v236, 26
	v_readlane_b32 s77, v236, 27
	v_readlane_b32 s78, v236, 28
	v_readlane_b32 s79, v236, 29
	v_readlane_b32 s80, v236, 30
	v_readlane_b32 s81, v236, 31
	v_readlane_b32 s82, v236, 32
	v_readlane_b32 s83, v236, 33
	v_readlane_b32 s84, v236, 34
	v_readlane_b32 s85, v236, 35
	v_readlane_b32 s86, v236, 36
	v_readlane_b32 s87, v236, 37
	s_nop 3
	s_nop 0
